# 4-phase merged K loops also for down-proj, w_out, ctx down, ctx gate/up and ctx w_out GEMMs (6 of 8 K loops merged)
# baseline (speedup 1.0000x reference)
; #define PG8_STAGE(bufoff, gbase, voff) do { _Pragma("unroll") for (int _i = 0; _i < 2; ++_i) \
;     __builtin_amdgcn_global_load_lds((const unsigned*)((const char*)(gbase) + (voff)[_i]), (LAS unsigned*)(lds + (bufoff) + ldsw + _i * 8192), 16, 0, 0); } while (0)
; #define PG8_LDA(dst, b, h) do { _Pragma("unroll") for (int m = 0; m < 4; ++m) _Pragma("unroll") for (int k = 0; k < 2; ++k) dst[m][k] = *(const LAS bf16x8*)(lds + PG8_SA(b, h) + aoff + m * 2048 + k * 1024); } while (0)
; #define PG8_LDB(dst, b, h) do { _Pragma("unroll") for (int n = 0; n < 2; ++n) _Pragma("unroll") for (int k = 0; k < 2; ++k) dst[n][k] = *(const LAS bf16x8*)(lds + PG8_SB(b, h) + boff + n * 2048 + k * 1024); } while (0)
; #define PG8_MMA(ai, bj, At, Bt) do { __builtin_amdgcn_s_setprio(1); _Pragma("unroll") for (int m = 0; m < 4; ++m) _Pragma("unroll") for (int n = 0; n < 2; ++n) _Pragma("unroll") for (int k = 0; k < 2; ++k) \
;     acc[ai][bj][m][n] = __builtin_amdgcn_mfma_f32_16x16x32_bf16(Bt[n][k], At[m][k], acc[ai][bj][m][n], 0, 0, 0); __builtin_amdgcn_s_setprio(0); } while (0)
; #define PG8_WAIT_V(n) asm volatile("s_waitcnt vmcnt(" #n ")" ::: "memory")
; #define PG8_WAIT_L(n) asm volatile("s_waitcnt lgkmcnt(" #n ")" ::: "memory")
; #define PG8_BAR __builtin_amdgcn_s_barrier()
; #define PG8_SCHED __builtin_amdgcn_sched_barrier(0)
; template <class Epi, class Sched>
; DI void gemm_phase(LAS unsigned char* lds, const Gemm g, const Sched& S, const Epi& E) {
;     ...
;       PG8_LDB(B0, 0, 0); PG8_SCHED; PG8_LDA(At, 0, 0); PG8_STAGE(PG8_SA(1, 1), a1 + hstep, voffA);
;       PG8_WAIT_L(8); PG8_BAR; PG8_WAIT_L(0); PG8_MMA(0, 0, At, B0); PG8_BAR; PG8_SCHED;
;       PG8_LDB(B1, 0, 1); PG8_STAGE(PG8_SB(0, 0), b2, voffB);
;       PG8_BAR; PG8_WAIT_L(0); PG8_MMA(0, 1, At, B1); PG8_BAR;
;       PG8_LDA(At, 0, 1); PG8_STAGE(PG8_SA(0, 0), a2, voffA);
;       PG8_BAR; PG8_WAIT_L(0); PG8_MMA(1, 0, At, B0); PG8_BAR; PG8_SCHED;
;       PG8_STAGE(PG8_SB(0, 1), b2 + hstepB, voffB);
;       PG8_WAIT_V(6); PG8_BAR; PG8_MMA(1, 1, At, B1); PG8_BAR;
.LBB0_137:
	s_add_i32 s41, s1, 2
	s_add_u32 s18, s16, 0x80
	s_addc_u32 s19, s17, 0
	s_cmp_lg_u32 s40, s1
	s_cselect_b32 s20, s18, 0
	s_cselect_b32 s1, s19, 0
	s_add_u32 s18, s14, s20
	s_addc_u32 s19, s15, s1
	s_add_i32 s42, 16, 0x10000
	v_add_u32_e32 v139, s42, v137
	ds_read_b128 v[140:143], v139
	ds_read_b128 v[144:147], v139 offset:1024
	ds_read_b128 v[150:153], v139 offset:2048
	ds_read_b128 v[154:157], v139 offset:3072
	s_add_u32 s20, s12, s20
	s_addc_u32 s21, s13, s1
	v_lshl_add_u64 v[180:181], v[132:133], 0, s[16:17]
	s_add_i32 m0, s31, 0xc000
	ds_read_b128 v[158:161], v138
	ds_read_b128 v[162:165], v138 offset:1024
	ds_read_b128 v[166:169], v138 offset:2048
	ds_read_b128 v[170:173], v138 offset:3072
	ds_read_b128 v[174:177], v138 offset:4096
	ds_read_b128 v[186:189], v138 offset:5120
	ds_read_b128 v[190:193], v138 offset:6144
	ds_read_b128 v[198:201], v138 offset:7168
	global_load_lds_dwordx4 v[180:181], off
	v_lshl_add_u64 v[180:181], v[134:135], 0, s[16:17]
	s_add_i32 m0, s31, 0xe000
	s_nop 0
	global_load_lds_dwordx4 v[180:181], off
	s_add_i32 s1, 16, 0x14000
	s_add_i32 s42, s42, s30
	v_add_u32_e32 v139, s1, v137
	ds_read_b128 v[202:205], v139
	ds_read_b128 v[206:209], v139 offset:1024
	ds_read_b128 v[214:217], v139 offset:2048
	ds_read_b128 v[218:221], v139 offset:3072
	s_waitcnt lgkmcnt(0)
	s_barrier
	v_mfma_f32_16x16x32_bf16 v[126:129], v[140:143], v[158:161], v[126:129]
	v_mfma_f32_16x16x32_bf16 v[122:125], v[150:153], v[158:161], v[122:125]
	v_mfma_f32_16x16x32_bf16 v[110:113], v[140:143], v[166:169], v[110:113]
	v_mfma_f32_16x16x32_bf16 v[106:109], v[150:153], v[166:169], v[106:109]
	v_mfma_f32_16x16x32_bf16 v[94:97], v[140:143], v[174:177], v[94:97]
	v_mfma_f32_16x16x32_bf16 v[90:93], v[150:153], v[174:177], v[90:93]
	v_mfma_f32_16x16x32_bf16 v[78:81], v[140:143], v[190:193], v[78:81]
	v_mfma_f32_16x16x32_bf16 v[74:77], v[150:153], v[190:193], v[74:77]
	v_mfma_f32_16x16x32_bf16 v[126:129], v[144:147], v[162:165], v[126:129]
	v_mfma_f32_16x16x32_bf16 v[122:125], v[154:157], v[162:165], v[122:125]
	v_mfma_f32_16x16x32_bf16 v[110:113], v[144:147], v[170:173], v[110:113]
	v_mfma_f32_16x16x32_bf16 v[106:109], v[154:157], v[170:173], v[106:109]
	v_mfma_f32_16x16x32_bf16 v[94:97], v[144:147], v[186:189], v[94:97]
	v_mfma_f32_16x16x32_bf16 v[90:93], v[154:157], v[186:189], v[90:93]
	v_mfma_f32_16x16x32_bf16 v[78:81], v[144:147], v[198:201], v[78:81]
	v_mfma_f32_16x16x32_bf16 v[74:77], v[154:157], v[198:201], v[74:77]
	v_mfma_f32_16x16x32_bf16 v[118:121], v[202:205], v[158:161], v[118:121]
	v_mfma_f32_16x16x32_bf16 v[114:117], v[214:217], v[158:161], v[114:117]
	v_mfma_f32_16x16x32_bf16 v[102:105], v[202:205], v[166:169], v[102:105]
	v_mfma_f32_16x16x32_bf16 v[98:101], v[214:217], v[166:169], v[98:101]
	v_mfma_f32_16x16x32_bf16 v[86:89], v[202:205], v[174:177], v[86:89]
	v_mfma_f32_16x16x32_bf16 v[82:85], v[214:217], v[174:177], v[82:85]
	v_mfma_f32_16x16x32_bf16 v[70:73], v[202:205], v[190:193], v[70:73]
	v_mfma_f32_16x16x32_bf16 v[66:69], v[214:217], v[190:193], v[66:69]
	v_mfma_f32_16x16x32_bf16 v[118:121], v[206:209], v[162:165], v[118:121]
	v_mfma_f32_16x16x32_bf16 v[114:117], v[218:221], v[162:165], v[114:117]
	v_mfma_f32_16x16x32_bf16 v[102:105], v[206:209], v[170:173], v[102:105]
	v_mfma_f32_16x16x32_bf16 v[98:101], v[218:221], v[170:173], v[98:101]
	v_mfma_f32_16x16x32_bf16 v[86:89], v[206:209], v[186:189], v[86:89]
	v_mfma_f32_16x16x32_bf16 v[82:85], v[218:221], v[186:189], v[82:85]
	v_mfma_f32_16x16x32_bf16 v[70:73], v[206:209], v[198:201], v[70:73]
	v_mfma_f32_16x16x32_bf16 v[66:69], v[218:221], v[198:201], v[66:69]
	s_mov_b32 m0, s31
	v_lshl_add_u64 v[184:185], s[18:19], 0, v[0:1]
	s_barrier
	ds_read_b128 v[158:161], v138 offset:16384
	ds_read_b128 v[162:165], v138 offset:17408
	ds_read_b128 v[166:169], v138 offset:18432
	ds_read_b128 v[170:173], v138 offset:19456
	ds_read_b128 v[174:177], v138 offset:20480
	ds_read_b128 v[186:189], v138 offset:21504
	ds_read_b128 v[190:193], v138 offset:22528
	ds_read_b128 v[198:201], v138 offset:23552
	global_load_lds_dwordx4 v[184:185], off
	v_lshl_add_u64 v[222:223], s[18:19], 0, v[130:131]
	s_mov_b32 m0, s34
	s_nop 0
	global_load_lds_dwordx4 v[222:223], off
	v_lshl_add_u64 v[230:231], s[20:21], 0, v[0:1]
	s_mov_b32 m0, s42
	s_nop 0
	global_load_lds_dwordx4 v[230:231], off
	v_lshl_add_u64 v[182:183], s[20:21], 0, v[130:131]
	s_add_i32 m0, s42, 0x2000
	s_nop 0
	global_load_lds_dwordx4 v[182:183], off
	s_add_u32 s20, s20, s2
	s_addc_u32 s21, s21, s3
	s_add_i32 s1, s1, s30
	v_lshl_add_u64 v[224:225], s[20:21], 0, v[0:1]
	s_mov_b32 m0, s1
	v_lshl_add_u64 v[226:227], s[20:21], 0, v[130:131]
	global_load_lds_dwordx4 v[224:225], off
	s_add_i32 m0, s1, 0x2000
	s_nop 0
	global_load_lds_dwordx4 v[226:227], off
	s_waitcnt vmcnt(6)
	s_waitcnt lgkmcnt(0)
	s_barrier
; #define PG8_STAGE(bufoff, gbase, voff) do { _Pragma("unroll") for (int _i = 0; _i < 2; ++_i) \
;     __builtin_amdgcn_global_load_lds((const unsigned*)((const char*)(gbase) + (voff)[_i]), (LAS unsigned*)(lds + (bufoff) + ldsw + _i * 8192), 16, 0, 0); } while (0)
; #define PG8_LDA(dst, b, h) do { _Pragma("unroll") for (int m = 0; m < 4; ++m) _Pragma("unroll") for (int k = 0; k < 2; ++k) dst[m][k] = *(const LAS bf16x8*)(lds + PG8_SA(b, h) + aoff + m * 2048 + k * 1024); } while (0)
; #define PG8_LDB(dst, b, h) do { _Pragma("unroll") for (int n = 0; n < 2; ++n) _Pragma("unroll") for (int k = 0; k < 2; ++k) dst[n][k] = *(const LAS bf16x8*)(lds + PG8_SB(b, h) + boff + n * 2048 + k * 1024); } while (0)
; #define PG8_MMA(ai, bj, At, Bt) do { __builtin_amdgcn_s_setprio(1); _Pragma("unroll") for (int m = 0; m < 4; ++m) _Pragma("unroll") for (int n = 0; n < 2; ++n) _Pragma("unroll") for (int k = 0; k < 2; ++k) \
;     acc[ai][bj][m][n] = __builtin_amdgcn_mfma_f32_16x16x32_bf16(Bt[n][k], At[m][k], acc[ai][bj][m][n], 0, 0, 0); __builtin_amdgcn_s_setprio(0); } while (0)
; #define PG8_WAIT_V(n) asm volatile("s_waitcnt vmcnt(" #n ")" ::: "memory")
; #define PG8_WAIT_L(n) asm volatile("s_waitcnt lgkmcnt(" #n ")" ::: "memory")
; #define PG8_BAR __builtin_amdgcn_s_barrier()
; #define PG8_SCHED __builtin_amdgcn_sched_barrier(0)
; template <class Epi, class Sched>
; DI void gemm_phase(LAS unsigned char* lds, const Gemm g, const Sched& S, const Epi& E) {
;     ...
;       PG8_WAIT_V(6); PG8_BAR; PG8_MMA(1, 1, At, B1); PG8_BAR;
;       PG8_LDB(B0, 1, 0); PG8_SCHED; PG8_LDA(At, 1, 0); PG8_STAGE(PG8_SA(0, 1), a2 + hstep, voffA);
;       PG8_WAIT_L(8); PG8_BAR; PG8_WAIT_L(0); PG8_MMA(0, 0, At, B0); PG8_BAR; PG8_SCHED;
;       PG8_LDB(B1, 1, 1); PG8_STAGE(PG8_SB(1, 0), b3, voffB);
;       PG8_BAR; PG8_WAIT_L(0); PG8_MMA(0, 1, At, B1); PG8_BAR;
;       PG8_LDA(At, 1, 1); PG8_STAGE(PG8_SA(1, 0), a3, voffA);
;       PG8_BAR; PG8_WAIT_L(0); PG8_MMA(1, 0, At, B0); PG8_BAR; PG8_SCHED;
	v_mfma_f32_16x16x32_bf16 v[62:65], v[140:143], v[158:161], v[62:65]
	v_mfma_f32_16x16x32_bf16 v[58:61], v[150:153], v[158:161], v[58:61]
	v_mfma_f32_16x16x32_bf16 v[46:49], v[140:143], v[166:169], v[46:49]
	v_mfma_f32_16x16x32_bf16 v[42:45], v[150:153], v[166:169], v[42:45]
	v_mfma_f32_16x16x32_bf16 v[30:33], v[140:143], v[174:177], v[30:33]
	v_mfma_f32_16x16x32_bf16 v[26:29], v[150:153], v[174:177], v[26:29]
	v_mfma_f32_16x16x32_bf16 v[14:17], v[140:143], v[190:193], v[14:17]
	v_mfma_f32_16x16x32_bf16 v[10:13], v[150:153], v[190:193], v[10:13]
	v_mfma_f32_16x16x32_bf16 v[62:65], v[144:147], v[162:165], v[62:65]
	v_mfma_f32_16x16x32_bf16 v[58:61], v[154:157], v[162:165], v[58:61]
	v_mfma_f32_16x16x32_bf16 v[46:49], v[144:147], v[170:173], v[46:49]
	v_mfma_f32_16x16x32_bf16 v[42:45], v[154:157], v[170:173], v[42:45]
	v_mfma_f32_16x16x32_bf16 v[30:33], v[144:147], v[186:189], v[30:33]
	v_mfma_f32_16x16x32_bf16 v[26:29], v[154:157], v[186:189], v[26:29]
	v_mfma_f32_16x16x32_bf16 v[14:17], v[144:147], v[198:201], v[14:17]
	v_mfma_f32_16x16x32_bf16 v[10:13], v[154:157], v[198:201], v[10:13]
	v_mfma_f32_16x16x32_bf16 v[54:57], v[202:205], v[158:161], v[54:57]
	v_mfma_f32_16x16x32_bf16 v[50:53], v[214:217], v[158:161], v[50:53]
	v_mfma_f32_16x16x32_bf16 v[38:41], v[202:205], v[166:169], v[38:41]
	v_mfma_f32_16x16x32_bf16 v[34:37], v[214:217], v[166:169], v[34:37]
	v_mfma_f32_16x16x32_bf16 v[22:25], v[202:205], v[174:177], v[22:25]
	v_mfma_f32_16x16x32_bf16 v[18:21], v[214:217], v[174:177], v[18:21]
	v_mfma_f32_16x16x32_bf16 v[6:9], v[202:205], v[190:193], v[6:9]
	v_mfma_f32_16x16x32_bf16 v[2:5], v[214:217], v[190:193], v[2:5]
	v_mfma_f32_16x16x32_bf16 v[54:57], v[206:209], v[162:165], v[54:57]
	v_mfma_f32_16x16x32_bf16 v[50:53], v[218:221], v[162:165], v[50:53]
	v_mfma_f32_16x16x32_bf16 v[38:41], v[206:209], v[170:173], v[38:41]
	v_mfma_f32_16x16x32_bf16 v[34:37], v[218:221], v[170:173], v[34:37]
	v_mfma_f32_16x16x32_bf16 v[22:25], v[206:209], v[186:189], v[22:25]
	v_mfma_f32_16x16x32_bf16 v[18:21], v[218:221], v[186:189], v[18:21]
	v_mfma_f32_16x16x32_bf16 v[6:9], v[206:209], v[198:201], v[6:9]
	v_mfma_f32_16x16x32_bf16 v[2:5], v[218:221], v[198:201], v[2:5]
	s_add_i32 s1, 16, 0x18000
	v_add_u32_e32 v139, s1, v137
	s_barrier
	ds_read_b128 v[140:143], v139
	ds_read_b128 v[144:147], v139 offset:1024
	ds_read_b128 v[150:153], v139 offset:2048
	ds_read_b128 v[154:157], v139 offset:3072
	s_add_u32 s18, s18, s2
	s_addc_u32 s19, s19, s3
	s_mov_b32 m0, s35
	v_lshl_add_u64 v[202:203], s[18:19], 0, v[0:1]
	ds_read_b128 v[158:161], v138 offset:32768
	ds_read_b128 v[162:165], v138 offset:33792
	ds_read_b128 v[166:169], v138 offset:34816
	ds_read_b128 v[170:173], v138 offset:35840
	ds_read_b128 v[174:177], v138 offset:36864
	ds_read_b128 v[186:189], v138 offset:37888
	ds_read_b128 v[190:193], v138 offset:38912
	ds_read_b128 v[198:201], v138 offset:39936
	global_load_lds_dwordx4 v[202:203], off
	v_lshl_add_u64 v[202:203], s[18:19], 0, v[130:131]
	s_mov_b32 m0, s36
	s_nop 0
	global_load_lds_dwordx4 v[202:203], off
	s_add_i32 s18, 16, 0x1c000
	s_add_i32 s1, s1, s30
	v_add_u32_e32 v139, s18, v137
	ds_read_b128 v[202:205], v139
	ds_read_b128 v[206:209], v139 offset:1024
	ds_read_b128 v[214:217], v139 offset:2048
	ds_read_b128 v[218:221], v139 offset:3072
	s_waitcnt lgkmcnt(0)
	s_barrier
	v_mfma_f32_16x16x32_bf16 v[126:129], v[140:143], v[158:161], v[126:129]
	v_mfma_f32_16x16x32_bf16 v[122:125], v[150:153], v[158:161], v[122:125]
	v_mfma_f32_16x16x32_bf16 v[110:113], v[140:143], v[166:169], v[110:113]
	v_mfma_f32_16x16x32_bf16 v[106:109], v[150:153], v[166:169], v[106:109]
	v_mfma_f32_16x16x32_bf16 v[94:97], v[140:143], v[174:177], v[94:97]
	v_mfma_f32_16x16x32_bf16 v[90:93], v[150:153], v[174:177], v[90:93]
	v_mfma_f32_16x16x32_bf16 v[78:81], v[140:143], v[190:193], v[78:81]
	v_mfma_f32_16x16x32_bf16 v[74:77], v[150:153], v[190:193], v[74:77]
	v_mfma_f32_16x16x32_bf16 v[126:129], v[144:147], v[162:165], v[126:129]
	v_mfma_f32_16x16x32_bf16 v[122:125], v[154:157], v[162:165], v[122:125]
	v_mfma_f32_16x16x32_bf16 v[110:113], v[144:147], v[170:173], v[110:113]
	v_mfma_f32_16x16x32_bf16 v[106:109], v[154:157], v[170:173], v[106:109]
	v_mfma_f32_16x16x32_bf16 v[94:97], v[144:147], v[186:189], v[94:97]
	v_mfma_f32_16x16x32_bf16 v[90:93], v[154:157], v[186:189], v[90:93]
	v_mfma_f32_16x16x32_bf16 v[78:81], v[144:147], v[198:201], v[78:81]
	v_mfma_f32_16x16x32_bf16 v[74:77], v[154:157], v[198:201], v[74:77]
	v_mfma_f32_16x16x32_bf16 v[118:121], v[202:205], v[158:161], v[118:121]
	v_mfma_f32_16x16x32_bf16 v[114:117], v[214:217], v[158:161], v[114:117]
	v_mfma_f32_16x16x32_bf16 v[102:105], v[202:205], v[166:169], v[102:105]
	v_mfma_f32_16x16x32_bf16 v[98:101], v[214:217], v[166:169], v[98:101]
	v_mfma_f32_16x16x32_bf16 v[86:89], v[202:205], v[174:177], v[86:89]
	v_mfma_f32_16x16x32_bf16 v[82:85], v[214:217], v[174:177], v[82:85]
	v_mfma_f32_16x16x32_bf16 v[70:73], v[202:205], v[190:193], v[70:73]
	v_mfma_f32_16x16x32_bf16 v[66:69], v[214:217], v[190:193], v[66:69]
	v_mfma_f32_16x16x32_bf16 v[118:121], v[206:209], v[162:165], v[118:121]
	v_mfma_f32_16x16x32_bf16 v[114:117], v[218:221], v[162:165], v[114:117]
	v_mfma_f32_16x16x32_bf16 v[102:105], v[206:209], v[170:173], v[102:105]
	v_mfma_f32_16x16x32_bf16 v[98:101], v[218:221], v[170:173], v[98:101]
	v_mfma_f32_16x16x32_bf16 v[86:89], v[206:209], v[186:189], v[86:89]
	v_mfma_f32_16x16x32_bf16 v[82:85], v[218:221], v[186:189], v[82:85]
	v_mfma_f32_16x16x32_bf16 v[70:73], v[206:209], v[198:201], v[70:73]
	v_mfma_f32_16x16x32_bf16 v[66:69], v[218:221], v[198:201], v[66:69]
	s_mov_b32 m0, s37
	v_lshl_add_u64 v[180:181], v[184:185], 0, s[70:71]
	s_barrier
; #define PG8_STAGE(bufoff, gbase, voff) do { _Pragma("unroll") for (int _i = 0; _i < 2; ++_i) \
;     __builtin_amdgcn_global_load_lds((const unsigned*)((const char*)(gbase) + (voff)[_i]), (LAS unsigned*)(lds + (bufoff) + ldsw + _i * 8192), 16, 0, 0); } while (0)
; #define PG8_LDA(dst, b, h) do { _Pragma("unroll") for (int m = 0; m < 4; ++m) _Pragma("unroll") for (int k = 0; k < 2; ++k) dst[m][k] = *(const LAS bf16x8*)(lds + PG8_SA(b, h) + aoff + m * 2048 + k * 1024); } while (0)
; #define PG8_MMA(ai, bj, At, Bt) do { __builtin_amdgcn_s_setprio(1); _Pragma("unroll") for (int m = 0; m < 4; ++m) _Pragma("unroll") for (int n = 0; n < 2; ++n) _Pragma("unroll") for (int k = 0; k < 2; ++k) \
;     acc[ai][bj][m][n] = __builtin_amdgcn_mfma_f32_16x16x32_bf16(Bt[n][k], At[m][k], acc[ai][bj][m][n], 0, 0, 0); __builtin_amdgcn_s_setprio(0); } while (0)
; #define PG8_WAIT_V(n) asm volatile("s_waitcnt vmcnt(" #n ")" ::: "memory")
; #define PG8_WAIT_L(n) asm volatile("s_waitcnt lgkmcnt(" #n ")" ::: "memory")
; #define PG8_BAR __builtin_amdgcn_s_barrier()
; #define PG8_SCHED __builtin_amdgcn_sched_barrier(0)
; template <class Epi, class Sched>
; DI void gemm_phase(LAS unsigned char* lds, const Gemm g, const Sched& S, const Epi& E) {
;     ...
;       PG8_LDA(At, 1, 1); PG8_STAGE(PG8_SA(1, 0), a3, voffA);
;       PG8_BAR; PG8_WAIT_L(0); PG8_MMA(1, 0, At, B0); PG8_BAR; PG8_SCHED;
;       PG8_STAGE(PG8_SB(1, 1), b3 + hstepB, voffB);
;       PG8_WAIT_V(6); PG8_BAR; PG8_MMA(1, 1, At, B1); PG8_BAR;
;     }
	ds_read_b128 v[158:161], v138 offset:49152
	ds_read_b128 v[162:165], v138 offset:50176
	ds_read_b128 v[166:169], v138 offset:51200
	ds_read_b128 v[170:173], v138 offset:52224
	ds_read_b128 v[174:177], v138 offset:53248
	ds_read_b128 v[186:189], v138 offset:54272
	ds_read_b128 v[190:193], v138 offset:55296
	ds_read_b128 v[198:201], v138 offset:56320
	global_load_lds_dwordx4 v[180:181], off
	v_lshl_add_u64 v[180:181], v[222:223], 0, s[70:71]
	s_mov_b32 m0, s38
	s_nop 0
	global_load_lds_dwordx4 v[180:181], off
	v_lshl_add_u64 v[230:231], v[230:231], 0, s[70:71]
	s_mov_b32 m0, s1
	s_nop 0
	global_load_lds_dwordx4 v[230:231], off
	v_lshl_add_u64 v[180:181], v[182:183], 0, s[70:71]
	s_add_i32 m0, s1, 0x2000
	s_nop 0
	global_load_lds_dwordx4 v[180:181], off
	s_add_i32 s1, s18, s30
	v_lshl_add_u64 v[232:233], v[224:225], 0, s[70:71]
	s_mov_b32 m0, s1
	s_nop 0
	global_load_lds_dwordx4 v[232:233], off
	v_lshl_add_u64 v[232:233], v[226:227], 0, s[70:71]
	s_add_i32 m0, s1, 0x2000
	s_nop 0
	global_load_lds_dwordx4 v[232:233], off
	s_waitcnt vmcnt(6)
	s_waitcnt lgkmcnt(0)
	s_barrier
	v_mfma_f32_16x16x32_bf16 v[62:65], v[140:143], v[158:161], v[62:65]
	v_mfma_f32_16x16x32_bf16 v[58:61], v[150:153], v[158:161], v[58:61]
	v_mfma_f32_16x16x32_bf16 v[46:49], v[140:143], v[166:169], v[46:49]
	v_mfma_f32_16x16x32_bf16 v[42:45], v[150:153], v[166:169], v[42:45]
	v_mfma_f32_16x16x32_bf16 v[30:33], v[140:143], v[174:177], v[30:33]
	v_mfma_f32_16x16x32_bf16 v[26:29], v[150:153], v[174:177], v[26:29]
	v_mfma_f32_16x16x32_bf16 v[14:17], v[140:143], v[190:193], v[14:17]
	v_mfma_f32_16x16x32_bf16 v[10:13], v[150:153], v[190:193], v[10:13]
	v_mfma_f32_16x16x32_bf16 v[62:65], v[144:147], v[162:165], v[62:65]
	v_mfma_f32_16x16x32_bf16 v[58:61], v[154:157], v[162:165], v[58:61]
	v_mfma_f32_16x16x32_bf16 v[46:49], v[144:147], v[170:173], v[46:49]
	v_mfma_f32_16x16x32_bf16 v[42:45], v[154:157], v[170:173], v[42:45]
	v_mfma_f32_16x16x32_bf16 v[30:33], v[144:147], v[186:189], v[30:33]
	v_mfma_f32_16x16x32_bf16 v[26:29], v[154:157], v[186:189], v[26:29]
	v_mfma_f32_16x16x32_bf16 v[14:17], v[144:147], v[198:201], v[14:17]
	v_mfma_f32_16x16x32_bf16 v[10:13], v[154:157], v[198:201], v[10:13]
	v_mfma_f32_16x16x32_bf16 v[54:57], v[202:205], v[158:161], v[54:57]
	v_mfma_f32_16x16x32_bf16 v[50:53], v[214:217], v[158:161], v[50:53]
	v_mfma_f32_16x16x32_bf16 v[38:41], v[202:205], v[166:169], v[38:41]
	v_mfma_f32_16x16x32_bf16 v[34:37], v[214:217], v[166:169], v[34:37]
	v_mfma_f32_16x16x32_bf16 v[22:25], v[202:205], v[174:177], v[22:25]
	v_mfma_f32_16x16x32_bf16 v[18:21], v[214:217], v[174:177], v[18:21]
	v_mfma_f32_16x16x32_bf16 v[6:9], v[202:205], v[190:193], v[6:9]
	v_mfma_f32_16x16x32_bf16 v[2:5], v[214:217], v[190:193], v[2:5]
	v_mfma_f32_16x16x32_bf16 v[54:57], v[206:209], v[162:165], v[54:57]
	v_mfma_f32_16x16x32_bf16 v[50:53], v[218:221], v[162:165], v[50:53]
	v_mfma_f32_16x16x32_bf16 v[38:41], v[206:209], v[170:173], v[38:41]
	v_mfma_f32_16x16x32_bf16 v[34:37], v[218:221], v[170:173], v[34:37]
	v_mfma_f32_16x16x32_bf16 v[22:25], v[206:209], v[186:189], v[22:25]
	v_mfma_f32_16x16x32_bf16 v[18:21], v[218:221], v[186:189], v[18:21]
	v_mfma_f32_16x16x32_bf16 v[6:9], v[206:209], v[198:201], v[6:9]
	v_mfma_f32_16x16x32_bf16 v[2:5], v[218:221], v[198:201], v[2:5]
	s_add_u32 s16, s16, 0x100
	s_addc_u32 s17, s17, 0
	s_cmp_ge_i32 s41, s39
	s_mov_b32 s1, s41
	s_barrier
	s_cbranch_scc0 .LBB0_137

; #define PG8_STAGE(bufoff, gbase, voff) do { _Pragma("unroll") for (int _i = 0; _i < 2; ++_i) \
;     __builtin_amdgcn_global_load_lds((const unsigned*)((const char*)(gbase) + (voff)[_i]), (LAS unsigned*)(lds + (bufoff) + ldsw + _i * 8192), 16, 0, 0); } while (0)
; #define PG8_LDA(dst, b, h) do { _Pragma("unroll") for (int m = 0; m < 4; ++m) _Pragma("unroll") for (int k = 0; k < 2; ++k) dst[m][k] = *(const LAS bf16x8*)(lds + PG8_SA(b, h) + aoff + m * 2048 + k * 1024); } while (0)
; #define PG8_LDB(dst, b, h) do { _Pragma("unroll") for (int n = 0; n < 2; ++n) _Pragma("unroll") for (int k = 0; k < 2; ++k) dst[n][k] = *(const LAS bf16x8*)(lds + PG8_SB(b, h) + boff + n * 2048 + k * 1024); } while (0)
; #define PG8_MMA(ai, bj, At, Bt) do { __builtin_amdgcn_s_setprio(1); _Pragma("unroll") for (int m = 0; m < 4; ++m) _Pragma("unroll") for (int n = 0; n < 2; ++n) _Pragma("unroll") for (int k = 0; k < 2; ++k) \
;     acc[ai][bj][m][n] = __builtin_amdgcn_mfma_f32_16x16x32_bf16(Bt[n][k], At[m][k], acc[ai][bj][m][n], 0, 0, 0); __builtin_amdgcn_s_setprio(0); } while (0)
; #define PG8_WAIT_V(n) asm volatile("s_waitcnt vmcnt(" #n ")" ::: "memory")
; #define PG8_WAIT_L(n) asm volatile("s_waitcnt lgkmcnt(" #n ")" ::: "memory")
; #define PG8_BAR __builtin_amdgcn_s_barrier()
; #define PG8_SCHED __builtin_amdgcn_sched_barrier(0)
; template <class Epi, class Sched>
; DI void gemm_phase(LAS unsigned char* lds, const Gemm g, const Sched& S, const Epi& E) {
;     ...
;       PG8_LDB(B0, 0, 0); PG8_SCHED; PG8_LDA(At, 0, 0); PG8_STAGE(PG8_SA(1, 1), a1 + hstep, voffA);
;       PG8_WAIT_L(8); PG8_BAR; PG8_WAIT_L(0); PG8_MMA(0, 0, At, B0); PG8_BAR; PG8_SCHED;
;       PG8_LDB(B1, 0, 1); PG8_STAGE(PG8_SB(0, 0), b2, voffB);
;       PG8_BAR; PG8_WAIT_L(0); PG8_MMA(0, 1, At, B1); PG8_BAR;
;       PG8_LDA(At, 0, 1); PG8_STAGE(PG8_SA(0, 0), a2, voffA);
;       PG8_BAR; PG8_WAIT_L(0); PG8_MMA(1, 0, At, B0); PG8_BAR; PG8_SCHED;
;       PG8_STAGE(PG8_SB(0, 1), b2 + hstepB, voffB);
;       PG8_WAIT_V(6); PG8_BAR; PG8_MMA(1, 1, At, B1); PG8_BAR;
.LBB0_153:
	s_add_i32 s36, s16, 2
	s_add_u32 s17, s14, 0xfa800080
	s_addc_u32 s18, s15, -1
	s_cmp_lg_u32 s35, s16
	s_cselect_b32 s19, s18, 0
	s_cselect_b32 s18, s17, 0
	s_add_u32 s16, s12, s18
	s_addc_u32 s17, s13, s19
	s_add_i32 s37, 16, 0x10000
	v_add_u32_e32 v139, s37, v137
	ds_read_b128 v[140:143], v139
	ds_read_b128 v[144:147], v139 offset:1024
	ds_read_b128 v[150:153], v139 offset:2048
	ds_read_b128 v[154:157], v139 offset:3072
	s_add_u32 s18, s2, s18
	s_addc_u32 s19, s3, s19
	v_lshl_add_u64 v[180:181], v[132:133], 0, s[14:15]
	s_add_i32 m0, s24, 0xc000
	ds_read_b128 v[158:161], v138
	ds_read_b128 v[162:165], v138 offset:1024
	ds_read_b128 v[166:169], v138 offset:2048
	ds_read_b128 v[170:173], v138 offset:3072
	ds_read_b128 v[174:177], v138 offset:4096
	ds_read_b128 v[186:189], v138 offset:5120
	ds_read_b128 v[190:193], v138 offset:6144
	ds_read_b128 v[198:201], v138 offset:7168
	global_load_lds_dwordx4 v[180:181], off
	v_lshl_add_u64 v[180:181], v[134:135], 0, s[14:15]
	s_add_i32 m0, s24, 0xe000
	s_nop 0
	global_load_lds_dwordx4 v[180:181], off
	s_add_i32 s38, 16, 0x14000
	s_add_i32 s37, s37, s23
	v_add_u32_e32 v139, s38, v137
	ds_read_b128 v[202:205], v139
	ds_read_b128 v[206:209], v139 offset:1024
	ds_read_b128 v[214:217], v139 offset:2048
	ds_read_b128 v[218:221], v139 offset:3072
	s_waitcnt lgkmcnt(0)
	s_barrier
	v_mfma_f32_16x16x32_bf16 v[126:129], v[140:143], v[158:161], v[126:129]
	v_mfma_f32_16x16x32_bf16 v[122:125], v[150:153], v[158:161], v[122:125]
	v_mfma_f32_16x16x32_bf16 v[110:113], v[140:143], v[166:169], v[110:113]
	v_mfma_f32_16x16x32_bf16 v[106:109], v[150:153], v[166:169], v[106:109]
	v_mfma_f32_16x16x32_bf16 v[94:97], v[140:143], v[174:177], v[94:97]
	v_mfma_f32_16x16x32_bf16 v[90:93], v[150:153], v[174:177], v[90:93]
	v_mfma_f32_16x16x32_bf16 v[78:81], v[140:143], v[190:193], v[78:81]
	v_mfma_f32_16x16x32_bf16 v[74:77], v[150:153], v[190:193], v[74:77]
	v_mfma_f32_16x16x32_bf16 v[126:129], v[144:147], v[162:165], v[126:129]
	v_mfma_f32_16x16x32_bf16 v[122:125], v[154:157], v[162:165], v[122:125]
	v_mfma_f32_16x16x32_bf16 v[110:113], v[144:147], v[170:173], v[110:113]
	v_mfma_f32_16x16x32_bf16 v[106:109], v[154:157], v[170:173], v[106:109]
	v_mfma_f32_16x16x32_bf16 v[94:97], v[144:147], v[186:189], v[94:97]
	v_mfma_f32_16x16x32_bf16 v[90:93], v[154:157], v[186:189], v[90:93]
	v_mfma_f32_16x16x32_bf16 v[78:81], v[144:147], v[198:201], v[78:81]
	v_mfma_f32_16x16x32_bf16 v[74:77], v[154:157], v[198:201], v[74:77]
	v_mfma_f32_16x16x32_bf16 v[118:121], v[202:205], v[158:161], v[118:121]
	v_mfma_f32_16x16x32_bf16 v[114:117], v[214:217], v[158:161], v[114:117]
	v_mfma_f32_16x16x32_bf16 v[102:105], v[202:205], v[166:169], v[102:105]
	v_mfma_f32_16x16x32_bf16 v[98:101], v[214:217], v[166:169], v[98:101]
	v_mfma_f32_16x16x32_bf16 v[86:89], v[202:205], v[174:177], v[86:89]
	v_mfma_f32_16x16x32_bf16 v[82:85], v[214:217], v[174:177], v[82:85]
	v_mfma_f32_16x16x32_bf16 v[70:73], v[202:205], v[190:193], v[70:73]
	v_mfma_f32_16x16x32_bf16 v[66:69], v[214:217], v[190:193], v[66:69]
	v_mfma_f32_16x16x32_bf16 v[118:121], v[206:209], v[162:165], v[118:121]
	v_mfma_f32_16x16x32_bf16 v[114:117], v[218:221], v[162:165], v[114:117]
	v_mfma_f32_16x16x32_bf16 v[102:105], v[206:209], v[170:173], v[102:105]
	v_mfma_f32_16x16x32_bf16 v[98:101], v[218:221], v[170:173], v[98:101]
	v_mfma_f32_16x16x32_bf16 v[86:89], v[206:209], v[186:189], v[86:89]
	v_mfma_f32_16x16x32_bf16 v[82:85], v[218:221], v[186:189], v[82:85]
	v_mfma_f32_16x16x32_bf16 v[70:73], v[206:209], v[198:201], v[70:73]
	v_mfma_f32_16x16x32_bf16 v[66:69], v[218:221], v[198:201], v[66:69]
	s_mov_b32 m0, s24
	v_lshl_add_u64 v[184:185], s[16:17], 0, v[0:1]
	s_barrier
	ds_read_b128 v[158:161], v138 offset:16384
	ds_read_b128 v[162:165], v138 offset:17408
	ds_read_b128 v[166:169], v138 offset:18432
	ds_read_b128 v[170:173], v138 offset:19456
	ds_read_b128 v[174:177], v138 offset:20480
	ds_read_b128 v[186:189], v138 offset:21504
	ds_read_b128 v[190:193], v138 offset:22528
	ds_read_b128 v[198:201], v138 offset:23552
	global_load_lds_dwordx4 v[184:185], off
	v_lshl_add_u64 v[222:223], s[16:17], 0, v[130:131]
	s_mov_b32 m0, s25
	s_nop 0
	global_load_lds_dwordx4 v[222:223], off
	v_lshl_add_u64 v[230:231], s[18:19], 0, v[0:1]
	s_mov_b32 m0, s37
	s_nop 0
	global_load_lds_dwordx4 v[230:231], off
	v_lshl_add_u64 v[182:183], s[18:19], 0, v[130:131]
	s_add_i32 m0, s37, 0x2000
	s_nop 0
	global_load_lds_dwordx4 v[182:183], off
	s_add_u32 s18, s18, s0
	s_addc_u32 s19, s19, s1
	s_add_i32 s37, s38, s23
	v_lshl_add_u64 v[224:225], s[18:19], 0, v[0:1]
	s_mov_b32 m0, s37
	v_lshl_add_u64 v[226:227], s[18:19], 0, v[130:131]
	global_load_lds_dwordx4 v[224:225], off
	s_add_i32 m0, s37, 0x2000
	s_nop 0
	global_load_lds_dwordx4 v[226:227], off
	s_waitcnt vmcnt(6)
	s_waitcnt lgkmcnt(0)
	s_barrier
; #define PG8_STAGE(bufoff, gbase, voff) do { _Pragma("unroll") for (int _i = 0; _i < 2; ++_i) \
;     __builtin_amdgcn_global_load_lds((const unsigned*)((const char*)(gbase) + (voff)[_i]), (LAS unsigned*)(lds + (bufoff) + ldsw + _i * 8192), 16, 0, 0); } while (0)
; #define PG8_LDA(dst, b, h) do { _Pragma("unroll") for (int m = 0; m < 4; ++m) _Pragma("unroll") for (int k = 0; k < 2; ++k) dst[m][k] = *(const LAS bf16x8*)(lds + PG8_SA(b, h) + aoff + m * 2048 + k * 1024); } while (0)
; #define PG8_LDB(dst, b, h) do { _Pragma("unroll") for (int n = 0; n < 2; ++n) _Pragma("unroll") for (int k = 0; k < 2; ++k) dst[n][k] = *(const LAS bf16x8*)(lds + PG8_SB(b, h) + boff + n * 2048 + k * 1024); } while (0)
; #define PG8_MMA(ai, bj, At, Bt) do { __builtin_amdgcn_s_setprio(1); _Pragma("unroll") for (int m = 0; m < 4; ++m) _Pragma("unroll") for (int n = 0; n < 2; ++n) _Pragma("unroll") for (int k = 0; k < 2; ++k) \
;     acc[ai][bj][m][n] = __builtin_amdgcn_mfma_f32_16x16x32_bf16(Bt[n][k], At[m][k], acc[ai][bj][m][n], 0, 0, 0); __builtin_amdgcn_s_setprio(0); } while (0)
; #define PG8_WAIT_V(n) asm volatile("s_waitcnt vmcnt(" #n ")" ::: "memory")
; #define PG8_WAIT_L(n) asm volatile("s_waitcnt lgkmcnt(" #n ")" ::: "memory")
; #define PG8_BAR __builtin_amdgcn_s_barrier()
; #define PG8_SCHED __builtin_amdgcn_sched_barrier(0)
; template <class Epi, class Sched>
; DI void gemm_phase(LAS unsigned char* lds, const Gemm g, const Sched& S, const Epi& E) {
;     ...
;       PG8_WAIT_V(6); PG8_BAR; PG8_MMA(1, 1, At, B1); PG8_BAR;
;       PG8_LDB(B0, 1, 0); PG8_SCHED; PG8_LDA(At, 1, 0); PG8_STAGE(PG8_SA(0, 1), a2 + hstep, voffA);
;       PG8_WAIT_L(8); PG8_BAR; PG8_WAIT_L(0); PG8_MMA(0, 0, At, B0); PG8_BAR; PG8_SCHED;
;       PG8_LDB(B1, 1, 1); PG8_STAGE(PG8_SB(1, 0), b3, voffB);
;       PG8_BAR; PG8_WAIT_L(0); PG8_MMA(0, 1, At, B1); PG8_BAR;
;       PG8_LDA(At, 1, 1); PG8_STAGE(PG8_SA(1, 0), a3, voffA);
;       PG8_BAR; PG8_WAIT_L(0); PG8_MMA(1, 0, At, B0); PG8_BAR; PG8_SCHED;
	v_mfma_f32_16x16x32_bf16 v[62:65], v[140:143], v[158:161], v[62:65]
	v_mfma_f32_16x16x32_bf16 v[58:61], v[150:153], v[158:161], v[58:61]
	v_mfma_f32_16x16x32_bf16 v[46:49], v[140:143], v[166:169], v[46:49]
	v_mfma_f32_16x16x32_bf16 v[42:45], v[150:153], v[166:169], v[42:45]
	v_mfma_f32_16x16x32_bf16 v[30:33], v[140:143], v[174:177], v[30:33]
	v_mfma_f32_16x16x32_bf16 v[26:29], v[150:153], v[174:177], v[26:29]
	v_mfma_f32_16x16x32_bf16 v[14:17], v[140:143], v[190:193], v[14:17]
	v_mfma_f32_16x16x32_bf16 v[10:13], v[150:153], v[190:193], v[10:13]
	v_mfma_f32_16x16x32_bf16 v[62:65], v[144:147], v[162:165], v[62:65]
	v_mfma_f32_16x16x32_bf16 v[58:61], v[154:157], v[162:165], v[58:61]
	v_mfma_f32_16x16x32_bf16 v[46:49], v[144:147], v[170:173], v[46:49]
	v_mfma_f32_16x16x32_bf16 v[42:45], v[154:157], v[170:173], v[42:45]
	v_mfma_f32_16x16x32_bf16 v[30:33], v[144:147], v[186:189], v[30:33]
	v_mfma_f32_16x16x32_bf16 v[26:29], v[154:157], v[186:189], v[26:29]
	v_mfma_f32_16x16x32_bf16 v[14:17], v[144:147], v[198:201], v[14:17]
	v_mfma_f32_16x16x32_bf16 v[10:13], v[154:157], v[198:201], v[10:13]
	v_mfma_f32_16x16x32_bf16 v[54:57], v[202:205], v[158:161], v[54:57]
	v_mfma_f32_16x16x32_bf16 v[50:53], v[214:217], v[158:161], v[50:53]
	v_mfma_f32_16x16x32_bf16 v[38:41], v[202:205], v[166:169], v[38:41]
	v_mfma_f32_16x16x32_bf16 v[34:37], v[214:217], v[166:169], v[34:37]
	v_mfma_f32_16x16x32_bf16 v[22:25], v[202:205], v[174:177], v[22:25]
	v_mfma_f32_16x16x32_bf16 v[18:21], v[214:217], v[174:177], v[18:21]
	v_mfma_f32_16x16x32_bf16 v[6:9], v[202:205], v[190:193], v[6:9]
	v_mfma_f32_16x16x32_bf16 v[2:5], v[214:217], v[190:193], v[2:5]
	v_mfma_f32_16x16x32_bf16 v[54:57], v[206:209], v[162:165], v[54:57]
	v_mfma_f32_16x16x32_bf16 v[50:53], v[218:221], v[162:165], v[50:53]
	v_mfma_f32_16x16x32_bf16 v[38:41], v[206:209], v[170:173], v[38:41]
	v_mfma_f32_16x16x32_bf16 v[34:37], v[218:221], v[170:173], v[34:37]
	v_mfma_f32_16x16x32_bf16 v[22:25], v[206:209], v[186:189], v[22:25]
	v_mfma_f32_16x16x32_bf16 v[18:21], v[218:221], v[186:189], v[18:21]
	v_mfma_f32_16x16x32_bf16 v[6:9], v[206:209], v[198:201], v[6:9]
	v_mfma_f32_16x16x32_bf16 v[2:5], v[218:221], v[198:201], v[2:5]
	s_add_i32 s18, 16, 0x18000
	v_add_u32_e32 v139, s18, v137
	s_barrier
	ds_read_b128 v[140:143], v139
	ds_read_b128 v[144:147], v139 offset:1024
	ds_read_b128 v[150:153], v139 offset:2048
	ds_read_b128 v[154:157], v139 offset:3072
	s_add_u32 s16, s16, s0
	s_addc_u32 s17, s17, s1
	s_mov_b32 m0, s26
	v_lshl_add_u64 v[202:203], s[16:17], 0, v[0:1]
	ds_read_b128 v[158:161], v138 offset:32768
	ds_read_b128 v[162:165], v138 offset:33792
	ds_read_b128 v[166:169], v138 offset:34816
	ds_read_b128 v[170:173], v138 offset:35840
	ds_read_b128 v[174:177], v138 offset:36864
	ds_read_b128 v[186:189], v138 offset:37888
	ds_read_b128 v[190:193], v138 offset:38912
	ds_read_b128 v[198:201], v138 offset:39936
	global_load_lds_dwordx4 v[202:203], off
	v_lshl_add_u64 v[202:203], s[16:17], 0, v[130:131]
	s_mov_b32 m0, s27
	s_nop 0
	global_load_lds_dwordx4 v[202:203], off
	s_add_i32 s16, 16, 0x1c000
	s_add_i32 s17, s18, s23
	v_add_u32_e32 v139, s16, v137
	ds_read_b128 v[202:205], v139
	ds_read_b128 v[206:209], v139 offset:1024
	ds_read_b128 v[214:217], v139 offset:2048
	ds_read_b128 v[218:221], v139 offset:3072
	s_waitcnt lgkmcnt(0)
	s_barrier
	v_mfma_f32_16x16x32_bf16 v[126:129], v[140:143], v[158:161], v[126:129]
	v_mfma_f32_16x16x32_bf16 v[122:125], v[150:153], v[158:161], v[122:125]
	v_mfma_f32_16x16x32_bf16 v[110:113], v[140:143], v[166:169], v[110:113]
	v_mfma_f32_16x16x32_bf16 v[106:109], v[150:153], v[166:169], v[106:109]
	v_mfma_f32_16x16x32_bf16 v[94:97], v[140:143], v[174:177], v[94:97]
	v_mfma_f32_16x16x32_bf16 v[90:93], v[150:153], v[174:177], v[90:93]
	v_mfma_f32_16x16x32_bf16 v[78:81], v[140:143], v[190:193], v[78:81]
	v_mfma_f32_16x16x32_bf16 v[74:77], v[150:153], v[190:193], v[74:77]
	v_mfma_f32_16x16x32_bf16 v[126:129], v[144:147], v[162:165], v[126:129]
	v_mfma_f32_16x16x32_bf16 v[122:125], v[154:157], v[162:165], v[122:125]
	v_mfma_f32_16x16x32_bf16 v[110:113], v[144:147], v[170:173], v[110:113]
	v_mfma_f32_16x16x32_bf16 v[106:109], v[154:157], v[170:173], v[106:109]
	v_mfma_f32_16x16x32_bf16 v[94:97], v[144:147], v[186:189], v[94:97]
	v_mfma_f32_16x16x32_bf16 v[90:93], v[154:157], v[186:189], v[90:93]
	v_mfma_f32_16x16x32_bf16 v[78:81], v[144:147], v[198:201], v[78:81]
	v_mfma_f32_16x16x32_bf16 v[74:77], v[154:157], v[198:201], v[74:77]
	v_mfma_f32_16x16x32_bf16 v[118:121], v[202:205], v[158:161], v[118:121]
	v_mfma_f32_16x16x32_bf16 v[114:117], v[214:217], v[158:161], v[114:117]
	v_mfma_f32_16x16x32_bf16 v[102:105], v[202:205], v[166:169], v[102:105]
	v_mfma_f32_16x16x32_bf16 v[98:101], v[214:217], v[166:169], v[98:101]
	v_mfma_f32_16x16x32_bf16 v[86:89], v[202:205], v[174:177], v[86:89]
	v_mfma_f32_16x16x32_bf16 v[82:85], v[214:217], v[174:177], v[82:85]
	v_mfma_f32_16x16x32_bf16 v[70:73], v[202:205], v[190:193], v[70:73]
	v_mfma_f32_16x16x32_bf16 v[66:69], v[214:217], v[190:193], v[66:69]
	v_mfma_f32_16x16x32_bf16 v[118:121], v[206:209], v[162:165], v[118:121]
	v_mfma_f32_16x16x32_bf16 v[114:117], v[218:221], v[162:165], v[114:117]
	v_mfma_f32_16x16x32_bf16 v[102:105], v[206:209], v[170:173], v[102:105]
	v_mfma_f32_16x16x32_bf16 v[98:101], v[218:221], v[170:173], v[98:101]
	v_mfma_f32_16x16x32_bf16 v[86:89], v[206:209], v[186:189], v[86:89]
	v_mfma_f32_16x16x32_bf16 v[82:85], v[218:221], v[186:189], v[82:85]
	v_mfma_f32_16x16x32_bf16 v[70:73], v[206:209], v[198:201], v[70:73]
	v_mfma_f32_16x16x32_bf16 v[66:69], v[218:221], v[198:201], v[66:69]
	s_mov_b32 m0, s30
	v_lshl_add_u64 v[180:181], v[184:185], 0, s[70:71]
	s_barrier
; #define PG8_STAGE(bufoff, gbase, voff) do { _Pragma("unroll") for (int _i = 0; _i < 2; ++_i) \
;     __builtin_amdgcn_global_load_lds((const unsigned*)((const char*)(gbase) + (voff)[_i]), (LAS unsigned*)(lds + (bufoff) + ldsw + _i * 8192), 16, 0, 0); } while (0)
; #define PG8_LDA(dst, b, h) do { _Pragma("unroll") for (int m = 0; m < 4; ++m) _Pragma("unroll") for (int k = 0; k < 2; ++k) dst[m][k] = *(const LAS bf16x8*)(lds + PG8_SA(b, h) + aoff + m * 2048 + k * 1024); } while (0)
; #define PG8_MMA(ai, bj, At, Bt) do { __builtin_amdgcn_s_setprio(1); _Pragma("unroll") for (int m = 0; m < 4; ++m) _Pragma("unroll") for (int n = 0; n < 2; ++n) _Pragma("unroll") for (int k = 0; k < 2; ++k) \
;     acc[ai][bj][m][n] = __builtin_amdgcn_mfma_f32_16x16x32_bf16(Bt[n][k], At[m][k], acc[ai][bj][m][n], 0, 0, 0); __builtin_amdgcn_s_setprio(0); } while (0)
; #define PG8_WAIT_V(n) asm volatile("s_waitcnt vmcnt(" #n ")" ::: "memory")
; #define PG8_WAIT_L(n) asm volatile("s_waitcnt lgkmcnt(" #n ")" ::: "memory")
; #define PG8_BAR __builtin_amdgcn_s_barrier()
; #define PG8_SCHED __builtin_amdgcn_sched_barrier(0)
; template <class Epi, class Sched>
; DI void gemm_phase(LAS unsigned char* lds, const Gemm g, const Sched& S, const Epi& E) {
;     ...
;       PG8_LDA(At, 1, 1); PG8_STAGE(PG8_SA(1, 0), a3, voffA);
;       PG8_BAR; PG8_WAIT_L(0); PG8_MMA(1, 0, At, B0); PG8_BAR; PG8_SCHED;
;       PG8_STAGE(PG8_SB(1, 1), b3 + hstepB, voffB);
;       PG8_WAIT_V(6); PG8_BAR; PG8_MMA(1, 1, At, B1); PG8_BAR;
;     }
	ds_read_b128 v[158:161], v138 offset:49152
	ds_read_b128 v[162:165], v138 offset:50176
	ds_read_b128 v[166:169], v138 offset:51200
	ds_read_b128 v[170:173], v138 offset:52224
	ds_read_b128 v[174:177], v138 offset:53248
	ds_read_b128 v[186:189], v138 offset:54272
	ds_read_b128 v[190:193], v138 offset:55296
	ds_read_b128 v[198:201], v138 offset:56320
	global_load_lds_dwordx4 v[180:181], off
	v_lshl_add_u64 v[180:181], v[222:223], 0, s[70:71]
	s_mov_b32 m0, s31
	s_nop 0
	global_load_lds_dwordx4 v[180:181], off
	v_lshl_add_u64 v[230:231], v[230:231], 0, s[70:71]
	s_mov_b32 m0, s17
	s_nop 0
	global_load_lds_dwordx4 v[230:231], off
	v_lshl_add_u64 v[180:181], v[182:183], 0, s[70:71]
	s_add_i32 m0, s17, 0x2000
	s_nop 0
	global_load_lds_dwordx4 v[180:181], off
	s_add_i32 s16, s16, s23
	v_lshl_add_u64 v[232:233], v[224:225], 0, s[70:71]
	s_mov_b32 m0, s16
	s_nop 0
	global_load_lds_dwordx4 v[232:233], off
	v_lshl_add_u64 v[232:233], v[226:227], 0, s[70:71]
	s_add_i32 m0, s16, 0x2000
	s_nop 0
	global_load_lds_dwordx4 v[232:233], off
	s_waitcnt vmcnt(6)
	s_waitcnt lgkmcnt(0)
	s_barrier
	v_mfma_f32_16x16x32_bf16 v[62:65], v[140:143], v[158:161], v[62:65]
	v_mfma_f32_16x16x32_bf16 v[58:61], v[150:153], v[158:161], v[58:61]
	v_mfma_f32_16x16x32_bf16 v[46:49], v[140:143], v[166:169], v[46:49]
	v_mfma_f32_16x16x32_bf16 v[42:45], v[150:153], v[166:169], v[42:45]
	v_mfma_f32_16x16x32_bf16 v[30:33], v[140:143], v[174:177], v[30:33]
	v_mfma_f32_16x16x32_bf16 v[26:29], v[150:153], v[174:177], v[26:29]
	v_mfma_f32_16x16x32_bf16 v[14:17], v[140:143], v[190:193], v[14:17]
	v_mfma_f32_16x16x32_bf16 v[10:13], v[150:153], v[190:193], v[10:13]
	v_mfma_f32_16x16x32_bf16 v[62:65], v[144:147], v[162:165], v[62:65]
	v_mfma_f32_16x16x32_bf16 v[58:61], v[154:157], v[162:165], v[58:61]
	v_mfma_f32_16x16x32_bf16 v[46:49], v[144:147], v[170:173], v[46:49]
	v_mfma_f32_16x16x32_bf16 v[42:45], v[154:157], v[170:173], v[42:45]
	v_mfma_f32_16x16x32_bf16 v[30:33], v[144:147], v[186:189], v[30:33]
	v_mfma_f32_16x16x32_bf16 v[26:29], v[154:157], v[186:189], v[26:29]
	v_mfma_f32_16x16x32_bf16 v[14:17], v[144:147], v[198:201], v[14:17]
	v_mfma_f32_16x16x32_bf16 v[10:13], v[154:157], v[198:201], v[10:13]
	v_mfma_f32_16x16x32_bf16 v[54:57], v[202:205], v[158:161], v[54:57]
	v_mfma_f32_16x16x32_bf16 v[50:53], v[214:217], v[158:161], v[50:53]
	v_mfma_f32_16x16x32_bf16 v[38:41], v[202:205], v[166:169], v[38:41]
	v_mfma_f32_16x16x32_bf16 v[34:37], v[214:217], v[166:169], v[34:37]
	v_mfma_f32_16x16x32_bf16 v[22:25], v[202:205], v[174:177], v[22:25]
	v_mfma_f32_16x16x32_bf16 v[18:21], v[214:217], v[174:177], v[18:21]
	v_mfma_f32_16x16x32_bf16 v[6:9], v[202:205], v[190:193], v[6:9]
	v_mfma_f32_16x16x32_bf16 v[2:5], v[214:217], v[190:193], v[2:5]
	v_mfma_f32_16x16x32_bf16 v[54:57], v[206:209], v[162:165], v[54:57]
	v_mfma_f32_16x16x32_bf16 v[50:53], v[218:221], v[162:165], v[50:53]
	v_mfma_f32_16x16x32_bf16 v[38:41], v[206:209], v[170:173], v[38:41]
	v_mfma_f32_16x16x32_bf16 v[34:37], v[218:221], v[170:173], v[34:37]
	v_mfma_f32_16x16x32_bf16 v[22:25], v[206:209], v[186:189], v[22:25]
	v_mfma_f32_16x16x32_bf16 v[18:21], v[218:221], v[186:189], v[18:21]
	v_mfma_f32_16x16x32_bf16 v[6:9], v[206:209], v[198:201], v[6:9]
	v_mfma_f32_16x16x32_bf16 v[2:5], v[218:221], v[198:201], v[2:5]
	s_add_u32 s14, s14, 0x100
	s_addc_u32 s15, s15, 0
	s_cmp_ge_i32 s36, s34
	s_mov_b32 s16, s36
	s_barrier
	s_cbranch_scc0 .LBB0_153

; #define PG8_STAGE(bufoff, gbase, voff) do { _Pragma("unroll") for (int _i = 0; _i < 2; ++_i) \
;     __builtin_amdgcn_global_load_lds((const unsigned*)((const char*)(gbase) + (voff)[_i]), (LAS unsigned*)(lds + (bufoff) + ldsw + _i * 8192), 16, 0, 0); } while (0)
; #define PG8_LDA(dst, b, h) do { _Pragma("unroll") for (int m = 0; m < 4; ++m) _Pragma("unroll") for (int k = 0; k < 2; ++k) dst[m][k] = *(const LAS bf16x8*)(lds + PG8_SA(b, h) + aoff + m * 2048 + k * 1024); } while (0)
; #define PG8_LDB(dst, b, h) do { _Pragma("unroll") for (int n = 0; n < 2; ++n) _Pragma("unroll") for (int k = 0; k < 2; ++k) dst[n][k] = *(const LAS bf16x8*)(lds + PG8_SB(b, h) + boff + n * 2048 + k * 1024); } while (0)
; #define PG8_MMA(ai, bj, At, Bt) do { __builtin_amdgcn_s_setprio(1); _Pragma("unroll") for (int m = 0; m < 4; ++m) _Pragma("unroll") for (int n = 0; n < 2; ++n) _Pragma("unroll") for (int k = 0; k < 2; ++k) \
;     acc[ai][bj][m][n] = __builtin_amdgcn_mfma_f32_16x16x32_bf16(Bt[n][k], At[m][k], acc[ai][bj][m][n], 0, 0, 0); __builtin_amdgcn_s_setprio(0); } while (0)
; #define PG8_WAIT_V(n) asm volatile("s_waitcnt vmcnt(" #n ")" ::: "memory")
; #define PG8_WAIT_L(n) asm volatile("s_waitcnt lgkmcnt(" #n ")" ::: "memory")
; #define PG8_BAR __builtin_amdgcn_s_barrier()
; #define PG8_SCHED __builtin_amdgcn_sched_barrier(0)
; template <class Epi, class Sched>
; DI void gemm_phase(LAS unsigned char* lds, const Gemm g, const Sched& S, const Epi& E) {
;     ...
;       PG8_LDB(B0, 0, 0); PG8_SCHED; PG8_LDA(At, 0, 0); PG8_STAGE(PG8_SA(1, 1), a1 + hstep, voffA);
;       PG8_WAIT_L(8); PG8_BAR; PG8_WAIT_L(0); PG8_MMA(0, 0, At, B0); PG8_BAR; PG8_SCHED;
;       PG8_LDB(B1, 0, 1); PG8_STAGE(PG8_SB(0, 0), b2, voffB);
;       PG8_BAR; PG8_WAIT_L(0); PG8_MMA(0, 1, At, B1); PG8_BAR;
;       PG8_LDA(At, 0, 1); PG8_STAGE(PG8_SA(0, 0), a2, voffA);
;       PG8_BAR; PG8_WAIT_L(0); PG8_MMA(1, 0, At, B0); PG8_BAR; PG8_SCHED;
;       PG8_STAGE(PG8_SB(0, 1), b2 + hstepB, voffB);
;       PG8_WAIT_V(6); PG8_BAR; PG8_MMA(1, 1, At, B1); PG8_BAR;
.LBB0_191:
	s_add_i32 s34, s16, 2
	s_add_u32 s17, s14, 0xfe000080
	s_addc_u32 s18, s15, -1
	s_cmp_lg_u32 s31, s16
	s_cselect_b32 s19, s18, 0
	s_cselect_b32 s18, s17, 0
	s_add_u32 s16, s12, s18
	s_addc_u32 s17, s13, s19
	s_add_i32 s35, 16, 0x10000
	v_add_u32_e32 v156, s35, v142
	ds_read_b128 v[144:147], v156
	ds_read_b128 v[148:151], v156 offset:1024
	ds_read_b128 v[152:155], v156 offset:2048
	ds_read_b128 v[156:159], v156 offset:3072
	s_add_u32 s18, s2, s18
	s_addc_u32 s19, s3, s19
	v_lshl_add_u64 v[176:177], v[136:137], 0, s[14:15]
	s_add_i32 m0, s23, 0xc000
	ds_read_b128 v[160:163], v143
	ds_read_b128 v[164:167], v143 offset:1024
	ds_read_b128 v[168:171], v143 offset:2048
	ds_read_b128 v[172:175], v143 offset:3072
	ds_read_b128 v[186:189], v143 offset:4096
	ds_read_b128 v[190:193], v143 offset:5120
	ds_read_b128 v[198:201], v143 offset:6144
	ds_read_b128 v[202:205], v143 offset:7168
	global_load_lds_dwordx4 v[176:177], off
	v_lshl_add_u64 v[176:177], v[138:139], 0, s[14:15]
	s_add_i32 m0, s23, 0xe000
	s_nop 0
	global_load_lds_dwordx4 v[176:177], off
	s_add_i32 s36, 16, 0x14000
	v_add_u32_e32 v176, s36, v142
	s_add_i32 s35, s35, s22
	ds_read_b128 v[206:209], v176
	ds_read_b128 v[214:217], v176 offset:1024
	ds_read_b128 v[218:221], v176 offset:2048
	ds_read_b128 v[222:225], v176 offset:3072
	s_waitcnt lgkmcnt(0)
	s_barrier
	v_mfma_f32_16x16x32_bf16 v[126:129], v[144:147], v[160:163], v[126:129]
	v_mfma_f32_16x16x32_bf16 v[118:121], v[152:155], v[160:163], v[118:121]
	v_mfma_f32_16x16x32_bf16 v[110:113], v[144:147], v[168:171], v[110:113]
	v_mfma_f32_16x16x32_bf16 v[102:105], v[152:155], v[168:171], v[102:105]
	v_mfma_f32_16x16x32_bf16 v[94:97], v[144:147], v[186:189], v[94:97]
	v_mfma_f32_16x16x32_bf16 v[86:89], v[152:155], v[186:189], v[86:89]
	v_mfma_f32_16x16x32_bf16 v[78:81], v[144:147], v[198:201], v[78:81]
	v_mfma_f32_16x16x32_bf16 v[70:73], v[152:155], v[198:201], v[70:73]
	v_mfma_f32_16x16x32_bf16 v[126:129], v[148:151], v[164:167], v[126:129]
	v_mfma_f32_16x16x32_bf16 v[118:121], v[156:159], v[164:167], v[118:121]
	v_mfma_f32_16x16x32_bf16 v[110:113], v[148:151], v[172:175], v[110:113]
	v_mfma_f32_16x16x32_bf16 v[102:105], v[156:159], v[172:175], v[102:105]
	v_mfma_f32_16x16x32_bf16 v[94:97], v[148:151], v[190:193], v[94:97]
	v_mfma_f32_16x16x32_bf16 v[86:89], v[156:159], v[190:193], v[86:89]
	v_mfma_f32_16x16x32_bf16 v[78:81], v[148:151], v[202:205], v[78:81]
	v_mfma_f32_16x16x32_bf16 v[70:73], v[156:159], v[202:205], v[70:73]
	v_mfma_f32_16x16x32_bf16 v[122:125], v[206:209], v[160:163], v[122:125]
	v_mfma_f32_16x16x32_bf16 v[114:117], v[218:221], v[160:163], v[114:117]
	v_mfma_f32_16x16x32_bf16 v[106:109], v[206:209], v[168:171], v[106:109]
	v_mfma_f32_16x16x32_bf16 v[98:101], v[218:221], v[168:171], v[98:101]
	v_mfma_f32_16x16x32_bf16 v[90:93], v[206:209], v[186:189], v[90:93]
	v_mfma_f32_16x16x32_bf16 v[82:85], v[218:221], v[186:189], v[82:85]
	v_mfma_f32_16x16x32_bf16 v[74:77], v[206:209], v[198:201], v[74:77]
	v_mfma_f32_16x16x32_bf16 v[66:69], v[218:221], v[198:201], v[66:69]
	v_mfma_f32_16x16x32_bf16 v[122:125], v[214:217], v[164:167], v[122:125]
	v_mfma_f32_16x16x32_bf16 v[114:117], v[222:225], v[164:167], v[114:117]
	v_mfma_f32_16x16x32_bf16 v[106:109], v[214:217], v[172:175], v[106:109]
	v_mfma_f32_16x16x32_bf16 v[98:101], v[222:225], v[172:175], v[98:101]
	v_mfma_f32_16x16x32_bf16 v[90:93], v[214:217], v[190:193], v[90:93]
	v_mfma_f32_16x16x32_bf16 v[82:85], v[222:225], v[190:193], v[82:85]
	v_mfma_f32_16x16x32_bf16 v[74:77], v[214:217], v[202:205], v[74:77]
	v_mfma_f32_16x16x32_bf16 v[66:69], v[222:225], v[202:205], v[66:69]
	s_mov_b32 m0, s23
	v_lshl_add_u64 v[182:183], s[16:17], 0, v[134:135]
	s_barrier
	ds_read_b128 v[160:163], v143 offset:16384
	ds_read_b128 v[164:167], v143 offset:17408
	ds_read_b128 v[168:171], v143 offset:18432
	ds_read_b128 v[172:175], v143 offset:19456
	ds_read_b128 v[186:189], v143 offset:20480
	ds_read_b128 v[190:193], v143 offset:21504
	ds_read_b128 v[198:201], v143 offset:22528
	ds_read_b128 v[202:205], v143 offset:23552
	global_load_lds_dwordx4 v[182:183], off
	v_lshl_add_u64 v[184:185], s[16:17], 0, v[132:133]
	s_mov_b32 m0, s24
	s_nop 0
	global_load_lds_dwordx4 v[184:185], off
	v_lshl_add_u64 v[230:231], s[18:19], 0, v[0:1]
	s_mov_b32 m0, s35
	v_lshl_add_u64 v[180:181], s[18:19], 0, v[130:131]
	global_load_lds_dwordx4 v[230:231], off
	s_add_i32 m0, s35, 0x2000
	s_nop 0
	global_load_lds_dwordx4 v[180:181], off
	s_add_u32 s18, s18, s0
	s_addc_u32 s19, s19, s1
	s_add_i32 s35, s36, s22
	v_lshl_add_u64 v[226:227], s[18:19], 0, v[0:1]
	s_mov_b32 m0, s35
	v_lshl_add_u64 v[228:229], s[18:19], 0, v[130:131]
	global_load_lds_dwordx4 v[226:227], off
	s_add_i32 m0, s35, 0x2000
	s_nop 0
	global_load_lds_dwordx4 v[228:229], off
	s_waitcnt vmcnt(6)
	s_waitcnt lgkmcnt(0)
	s_barrier
; #define PG8_STAGE(bufoff, gbase, voff) do { _Pragma("unroll") for (int _i = 0; _i < 2; ++_i) \
;     __builtin_amdgcn_global_load_lds((const unsigned*)((const char*)(gbase) + (voff)[_i]), (LAS unsigned*)(lds + (bufoff) + ldsw + _i * 8192), 16, 0, 0); } while (0)
; #define PG8_LDA(dst, b, h) do { _Pragma("unroll") for (int m = 0; m < 4; ++m) _Pragma("unroll") for (int k = 0; k < 2; ++k) dst[m][k] = *(const LAS bf16x8*)(lds + PG8_SA(b, h) + aoff + m * 2048 + k * 1024); } while (0)
; #define PG8_LDB(dst, b, h) do { _Pragma("unroll") for (int n = 0; n < 2; ++n) _Pragma("unroll") for (int k = 0; k < 2; ++k) dst[n][k] = *(const LAS bf16x8*)(lds + PG8_SB(b, h) + boff + n * 2048 + k * 1024); } while (0)
; #define PG8_MMA(ai, bj, At, Bt) do { __builtin_amdgcn_s_setprio(1); _Pragma("unroll") for (int m = 0; m < 4; ++m) _Pragma("unroll") for (int n = 0; n < 2; ++n) _Pragma("unroll") for (int k = 0; k < 2; ++k) \
;     acc[ai][bj][m][n] = __builtin_amdgcn_mfma_f32_16x16x32_bf16(Bt[n][k], At[m][k], acc[ai][bj][m][n], 0, 0, 0); __builtin_amdgcn_s_setprio(0); } while (0)
; #define PG8_WAIT_V(n) asm volatile("s_waitcnt vmcnt(" #n ")" ::: "memory")
; #define PG8_WAIT_L(n) asm volatile("s_waitcnt lgkmcnt(" #n ")" ::: "memory")
; #define PG8_BAR __builtin_amdgcn_s_barrier()
; #define PG8_SCHED __builtin_amdgcn_sched_barrier(0)
; template <class Epi, class Sched>
; DI void gemm_phase(LAS unsigned char* lds, const Gemm g, const Sched& S, const Epi& E) {
;     ...
;       PG8_WAIT_V(6); PG8_BAR; PG8_MMA(1, 1, At, B1); PG8_BAR;
;       PG8_LDB(B0, 1, 0); PG8_SCHED; PG8_LDA(At, 1, 0); PG8_STAGE(PG8_SA(0, 1), a2 + hstep, voffA);
;       PG8_WAIT_L(8); PG8_BAR; PG8_WAIT_L(0); PG8_MMA(0, 0, At, B0); PG8_BAR; PG8_SCHED;
;       PG8_LDB(B1, 1, 1); PG8_STAGE(PG8_SB(1, 0), b3, voffB);
;       PG8_BAR; PG8_WAIT_L(0); PG8_MMA(0, 1, At, B1); PG8_BAR;
;       PG8_LDA(At, 1, 1); PG8_STAGE(PG8_SA(1, 0), a3, voffA);
;       PG8_BAR; PG8_WAIT_L(0); PG8_MMA(1, 0, At, B0); PG8_BAR; PG8_SCHED;
	v_mfma_f32_16x16x32_bf16 v[62:65], v[144:147], v[160:163], v[62:65]
	v_mfma_f32_16x16x32_bf16 v[54:57], v[152:155], v[160:163], v[54:57]
	v_mfma_f32_16x16x32_bf16 v[46:49], v[144:147], v[168:171], v[46:49]
	v_mfma_f32_16x16x32_bf16 v[38:41], v[152:155], v[168:171], v[38:41]
	v_mfma_f32_16x16x32_bf16 v[30:33], v[144:147], v[186:189], v[30:33]
	v_mfma_f32_16x16x32_bf16 v[22:25], v[152:155], v[186:189], v[22:25]
	v_mfma_f32_16x16x32_bf16 v[14:17], v[144:147], v[198:201], v[14:17]
	v_mfma_f32_16x16x32_bf16 v[6:9], v[152:155], v[198:201], v[6:9]
	v_mfma_f32_16x16x32_bf16 v[62:65], v[148:151], v[164:167], v[62:65]
	v_mfma_f32_16x16x32_bf16 v[54:57], v[156:159], v[164:167], v[54:57]
	v_mfma_f32_16x16x32_bf16 v[46:49], v[148:151], v[172:175], v[46:49]
	v_mfma_f32_16x16x32_bf16 v[38:41], v[156:159], v[172:175], v[38:41]
	v_mfma_f32_16x16x32_bf16 v[30:33], v[148:151], v[190:193], v[30:33]
	v_mfma_f32_16x16x32_bf16 v[22:25], v[156:159], v[190:193], v[22:25]
	v_mfma_f32_16x16x32_bf16 v[14:17], v[148:151], v[202:205], v[14:17]
	v_mfma_f32_16x16x32_bf16 v[6:9], v[156:159], v[202:205], v[6:9]
	v_mfma_f32_16x16x32_bf16 v[58:61], v[206:209], v[160:163], v[58:61]
	v_mfma_f32_16x16x32_bf16 v[50:53], v[218:221], v[160:163], v[50:53]
	v_mfma_f32_16x16x32_bf16 v[42:45], v[206:209], v[168:171], v[42:45]
	v_mfma_f32_16x16x32_bf16 v[34:37], v[218:221], v[168:171], v[34:37]
	v_mfma_f32_16x16x32_bf16 v[26:29], v[206:209], v[186:189], v[26:29]
	v_mfma_f32_16x16x32_bf16 v[18:21], v[218:221], v[186:189], v[18:21]
	v_mfma_f32_16x16x32_bf16 v[10:13], v[206:209], v[198:201], v[10:13]
	v_mfma_f32_16x16x32_bf16 v[2:5], v[218:221], v[198:201], v[2:5]
	v_mfma_f32_16x16x32_bf16 v[58:61], v[214:217], v[164:167], v[58:61]
	v_mfma_f32_16x16x32_bf16 v[50:53], v[222:225], v[164:167], v[50:53]
	v_mfma_f32_16x16x32_bf16 v[42:45], v[214:217], v[172:175], v[42:45]
	v_mfma_f32_16x16x32_bf16 v[34:37], v[222:225], v[172:175], v[34:37]
	v_mfma_f32_16x16x32_bf16 v[26:29], v[214:217], v[190:193], v[26:29]
	v_mfma_f32_16x16x32_bf16 v[18:21], v[222:225], v[190:193], v[18:21]
	v_mfma_f32_16x16x32_bf16 v[10:13], v[214:217], v[202:205], v[10:13]
	v_mfma_f32_16x16x32_bf16 v[2:5], v[222:225], v[202:205], v[2:5]
	s_add_i32 s18, 16, 0x18000
	v_add_u32_e32 v156, s18, v142
	s_barrier
	ds_read_b128 v[144:147], v156
	ds_read_b128 v[148:151], v156 offset:1024
	ds_read_b128 v[152:155], v156 offset:2048
	ds_read_b128 v[156:159], v156 offset:3072
	s_add_u32 s16, s16, s0
	s_addc_u32 s17, s17, s1
	s_mov_b32 m0, s25
	v_lshl_add_u64 v[206:207], s[16:17], 0, v[134:135]
	ds_read_b128 v[160:163], v143 offset:32768
	ds_read_b128 v[164:167], v143 offset:33792
	ds_read_b128 v[168:171], v143 offset:34816
	ds_read_b128 v[172:175], v143 offset:35840
	ds_read_b128 v[186:189], v143 offset:36864
	ds_read_b128 v[190:193], v143 offset:37888
	ds_read_b128 v[198:201], v143 offset:38912
	ds_read_b128 v[202:205], v143 offset:39936
	global_load_lds_dwordx4 v[206:207], off
	v_lshl_add_u64 v[206:207], s[16:17], 0, v[132:133]
	s_mov_b32 m0, s26
	s_nop 0
	global_load_lds_dwordx4 v[206:207], off
	s_add_i32 s16, 16, 0x1c000
	s_add_i32 s17, s18, s22
	v_add_u32_e32 v194, s16, v142
	ds_read_b128 v[206:209], v194
	ds_read_b128 v[214:217], v194 offset:1024
	ds_read_b128 v[218:221], v194 offset:2048
	ds_read_b128 v[222:225], v194 offset:3072
	s_waitcnt lgkmcnt(0)
	s_barrier
	v_mfma_f32_16x16x32_bf16 v[126:129], v[144:147], v[160:163], v[126:129]
	v_mfma_f32_16x16x32_bf16 v[118:121], v[152:155], v[160:163], v[118:121]
	v_mfma_f32_16x16x32_bf16 v[110:113], v[144:147], v[168:171], v[110:113]
	v_mfma_f32_16x16x32_bf16 v[102:105], v[152:155], v[168:171], v[102:105]
	v_mfma_f32_16x16x32_bf16 v[94:97], v[144:147], v[186:189], v[94:97]
	v_mfma_f32_16x16x32_bf16 v[86:89], v[152:155], v[186:189], v[86:89]
	v_mfma_f32_16x16x32_bf16 v[78:81], v[144:147], v[198:201], v[78:81]
	v_mfma_f32_16x16x32_bf16 v[70:73], v[152:155], v[198:201], v[70:73]
	v_mfma_f32_16x16x32_bf16 v[126:129], v[148:151], v[164:167], v[126:129]
	v_mfma_f32_16x16x32_bf16 v[118:121], v[156:159], v[164:167], v[118:121]
	v_mfma_f32_16x16x32_bf16 v[110:113], v[148:151], v[172:175], v[110:113]
	v_mfma_f32_16x16x32_bf16 v[102:105], v[156:159], v[172:175], v[102:105]
	v_mfma_f32_16x16x32_bf16 v[94:97], v[148:151], v[190:193], v[94:97]
	v_mfma_f32_16x16x32_bf16 v[86:89], v[156:159], v[190:193], v[86:89]
	v_mfma_f32_16x16x32_bf16 v[78:81], v[148:151], v[202:205], v[78:81]
	v_mfma_f32_16x16x32_bf16 v[70:73], v[156:159], v[202:205], v[70:73]
	v_mfma_f32_16x16x32_bf16 v[122:125], v[206:209], v[160:163], v[122:125]
	v_mfma_f32_16x16x32_bf16 v[114:117], v[218:221], v[160:163], v[114:117]
	v_mfma_f32_16x16x32_bf16 v[106:109], v[206:209], v[168:171], v[106:109]
	v_mfma_f32_16x16x32_bf16 v[98:101], v[218:221], v[168:171], v[98:101]
	v_mfma_f32_16x16x32_bf16 v[90:93], v[206:209], v[186:189], v[90:93]
	v_mfma_f32_16x16x32_bf16 v[82:85], v[218:221], v[186:189], v[82:85]
	v_mfma_f32_16x16x32_bf16 v[74:77], v[206:209], v[198:201], v[74:77]
	v_mfma_f32_16x16x32_bf16 v[66:69], v[218:221], v[198:201], v[66:69]
	v_mfma_f32_16x16x32_bf16 v[122:125], v[214:217], v[164:167], v[122:125]
	v_mfma_f32_16x16x32_bf16 v[114:117], v[222:225], v[164:167], v[114:117]
	v_mfma_f32_16x16x32_bf16 v[106:109], v[214:217], v[172:175], v[106:109]
	v_mfma_f32_16x16x32_bf16 v[98:101], v[222:225], v[172:175], v[98:101]
	v_mfma_f32_16x16x32_bf16 v[90:93], v[214:217], v[190:193], v[90:93]
	v_mfma_f32_16x16x32_bf16 v[82:85], v[222:225], v[190:193], v[82:85]
	v_mfma_f32_16x16x32_bf16 v[74:77], v[214:217], v[202:205], v[74:77]
	v_mfma_f32_16x16x32_bf16 v[66:69], v[222:225], v[202:205], v[66:69]
	s_mov_b32 m0, s27
	v_lshl_add_u64 v[176:177], v[182:183], 0, s[70:71]
	s_barrier
; #define PG8_STAGE(bufoff, gbase, voff) do { _Pragma("unroll") for (int _i = 0; _i < 2; ++_i) \
;     __builtin_amdgcn_global_load_lds((const unsigned*)((const char*)(gbase) + (voff)[_i]), (LAS unsigned*)(lds + (bufoff) + ldsw + _i * 8192), 16, 0, 0); } while (0)
; #define PG8_LDA(dst, b, h) do { _Pragma("unroll") for (int m = 0; m < 4; ++m) _Pragma("unroll") for (int k = 0; k < 2; ++k) dst[m][k] = *(const LAS bf16x8*)(lds + PG8_SA(b, h) + aoff + m * 2048 + k * 1024); } while (0)
; #define PG8_MMA(ai, bj, At, Bt) do { __builtin_amdgcn_s_setprio(1); _Pragma("unroll") for (int m = 0; m < 4; ++m) _Pragma("unroll") for (int n = 0; n < 2; ++n) _Pragma("unroll") for (int k = 0; k < 2; ++k) \
;     acc[ai][bj][m][n] = __builtin_amdgcn_mfma_f32_16x16x32_bf16(Bt[n][k], At[m][k], acc[ai][bj][m][n], 0, 0, 0); __builtin_amdgcn_s_setprio(0); } while (0)
; #define PG8_WAIT_V(n) asm volatile("s_waitcnt vmcnt(" #n ")" ::: "memory")
; #define PG8_WAIT_L(n) asm volatile("s_waitcnt lgkmcnt(" #n ")" ::: "memory")
; #define PG8_BAR __builtin_amdgcn_s_barrier()
; #define PG8_SCHED __builtin_amdgcn_sched_barrier(0)
; template <class Epi, class Sched>
; DI void gemm_phase(LAS unsigned char* lds, const Gemm g, const Sched& S, const Epi& E) {
;     ...
;       PG8_LDA(At, 1, 1); PG8_STAGE(PG8_SA(1, 0), a3, voffA);
;       PG8_BAR; PG8_WAIT_L(0); PG8_MMA(1, 0, At, B0); PG8_BAR; PG8_SCHED;
;       PG8_STAGE(PG8_SB(1, 1), b3 + hstepB, voffB);
;       PG8_WAIT_V(6); PG8_BAR; PG8_MMA(1, 1, At, B1); PG8_BAR;
;     }
	ds_read_b128 v[160:163], v143 offset:49152
	ds_read_b128 v[164:167], v143 offset:50176
	ds_read_b128 v[168:171], v143 offset:51200
	ds_read_b128 v[172:175], v143 offset:52224
	ds_read_b128 v[186:189], v143 offset:53248
	ds_read_b128 v[190:193], v143 offset:54272
	ds_read_b128 v[198:201], v143 offset:55296
	ds_read_b128 v[202:205], v143 offset:56320
	global_load_lds_dwordx4 v[176:177], off
	v_lshl_add_u64 v[176:177], v[184:185], 0, s[70:71]
	s_mov_b32 m0, s29
	s_nop 0
	global_load_lds_dwordx4 v[176:177], off
	v_lshl_add_u64 v[230:231], v[230:231], 0, s[70:71]
	s_mov_b32 m0, s17
	s_nop 0
	global_load_lds_dwordx4 v[230:231], off
	v_lshl_add_u64 v[176:177], v[180:181], 0, s[70:71]
	s_add_i32 m0, s17, 0x2000
	s_nop 0
	global_load_lds_dwordx4 v[176:177], off
	s_add_i32 s16, s16, s22
	v_lshl_add_u64 v[232:233], v[226:227], 0, s[70:71]
	s_mov_b32 m0, s16
	s_nop 0
	global_load_lds_dwordx4 v[232:233], off
	v_lshl_add_u64 v[232:233], v[228:229], 0, s[70:71]
	s_add_i32 m0, s16, 0x2000
	s_nop 0
	global_load_lds_dwordx4 v[232:233], off
	s_waitcnt vmcnt(6)
	s_waitcnt lgkmcnt(0)
	s_barrier
	v_mfma_f32_16x16x32_bf16 v[62:65], v[144:147], v[160:163], v[62:65]
	v_mfma_f32_16x16x32_bf16 v[54:57], v[152:155], v[160:163], v[54:57]
	v_mfma_f32_16x16x32_bf16 v[46:49], v[144:147], v[168:171], v[46:49]
	v_mfma_f32_16x16x32_bf16 v[38:41], v[152:155], v[168:171], v[38:41]
	v_mfma_f32_16x16x32_bf16 v[30:33], v[144:147], v[186:189], v[30:33]
	v_mfma_f32_16x16x32_bf16 v[22:25], v[152:155], v[186:189], v[22:25]
	v_mfma_f32_16x16x32_bf16 v[14:17], v[144:147], v[198:201], v[14:17]
	v_mfma_f32_16x16x32_bf16 v[6:9], v[152:155], v[198:201], v[6:9]
	v_mfma_f32_16x16x32_bf16 v[62:65], v[148:151], v[164:167], v[62:65]
	v_mfma_f32_16x16x32_bf16 v[54:57], v[156:159], v[164:167], v[54:57]
	v_mfma_f32_16x16x32_bf16 v[46:49], v[148:151], v[172:175], v[46:49]
	v_mfma_f32_16x16x32_bf16 v[38:41], v[156:159], v[172:175], v[38:41]
	v_mfma_f32_16x16x32_bf16 v[30:33], v[148:151], v[190:193], v[30:33]
	v_mfma_f32_16x16x32_bf16 v[22:25], v[156:159], v[190:193], v[22:25]
	v_mfma_f32_16x16x32_bf16 v[14:17], v[148:151], v[202:205], v[14:17]
	v_mfma_f32_16x16x32_bf16 v[6:9], v[156:159], v[202:205], v[6:9]
	v_mfma_f32_16x16x32_bf16 v[58:61], v[206:209], v[160:163], v[58:61]
	v_mfma_f32_16x16x32_bf16 v[50:53], v[218:221], v[160:163], v[50:53]
	v_mfma_f32_16x16x32_bf16 v[42:45], v[206:209], v[168:171], v[42:45]
	v_mfma_f32_16x16x32_bf16 v[34:37], v[218:221], v[168:171], v[34:37]
	v_mfma_f32_16x16x32_bf16 v[26:29], v[206:209], v[186:189], v[26:29]
	v_mfma_f32_16x16x32_bf16 v[18:21], v[218:221], v[186:189], v[18:21]
	v_mfma_f32_16x16x32_bf16 v[10:13], v[206:209], v[198:201], v[10:13]
	v_mfma_f32_16x16x32_bf16 v[2:5], v[218:221], v[198:201], v[2:5]
	v_mfma_f32_16x16x32_bf16 v[58:61], v[214:217], v[164:167], v[58:61]
	v_mfma_f32_16x16x32_bf16 v[50:53], v[222:225], v[164:167], v[50:53]
	v_mfma_f32_16x16x32_bf16 v[42:45], v[214:217], v[172:175], v[42:45]
	v_mfma_f32_16x16x32_bf16 v[34:37], v[222:225], v[172:175], v[34:37]
	v_mfma_f32_16x16x32_bf16 v[26:29], v[214:217], v[190:193], v[26:29]
	v_mfma_f32_16x16x32_bf16 v[18:21], v[222:225], v[190:193], v[18:21]
	v_mfma_f32_16x16x32_bf16 v[10:13], v[214:217], v[202:205], v[10:13]
	v_mfma_f32_16x16x32_bf16 v[2:5], v[222:225], v[202:205], v[2:5]
	s_add_u32 s14, s14, 0x100
	s_addc_u32 s15, s15, 0
	s_cmp_ge_i32 s34, s30
	s_mov_b32 s16, s34
	s_barrier
	s_cbranch_scc0 .LBB0_191

; #define PG8_STAGE(bufoff, gbase, voff) do { _Pragma("unroll") for (int _i = 0; _i < 2; ++_i) \
;     __builtin_amdgcn_global_load_lds((const unsigned*)((const char*)(gbase) + (voff)[_i]), (LAS unsigned*)(lds + (bufoff) + ldsw + _i * 8192), 16, 0, 0); } while (0)
; #define PG8_LDA(dst, b, h) do { _Pragma("unroll") for (int m = 0; m < 4; ++m) _Pragma("unroll") for (int k = 0; k < 2; ++k) dst[m][k] = *(const LAS bf16x8*)(lds + PG8_SA(b, h) + aoff + m * 2048 + k * 1024); } while (0)
; #define PG8_LDB(dst, b, h) do { _Pragma("unroll") for (int n = 0; n < 2; ++n) _Pragma("unroll") for (int k = 0; k < 2; ++k) dst[n][k] = *(const LAS bf16x8*)(lds + PG8_SB(b, h) + boff + n * 2048 + k * 1024); } while (0)
; #define PG8_MMA(ai, bj, At, Bt) do { __builtin_amdgcn_s_setprio(1); _Pragma("unroll") for (int m = 0; m < 4; ++m) _Pragma("unroll") for (int n = 0; n < 2; ++n) _Pragma("unroll") for (int k = 0; k < 2; ++k) \
;     acc[ai][bj][m][n] = __builtin_amdgcn_mfma_f32_16x16x32_bf16(Bt[n][k], At[m][k], acc[ai][bj][m][n], 0, 0, 0); __builtin_amdgcn_s_setprio(0); } while (0)
; #define PG8_WAIT_L(n) asm volatile("s_waitcnt lgkmcnt(" #n ")" ::: "memory")
; #define PG8_BAR __builtin_amdgcn_s_barrier()
; #define PG8_SCHED __builtin_amdgcn_sched_barrier(0)
; template <class Epi, class Sched>
; DI void gemm_phase(LAS unsigned char* lds, const Gemm g, const Sched& S, const Epi& E) {
;     ...
;     for (int t = 0; t < nt; t += 2) {
;       const bool last = (t == nt - 2);
;       const char* a1 = cA + (size_t)(t + 1) * kstep;
;       const char* a2 = last ? nA : cA + (size_t)(t + 2) * kstep; const char* b2 = last ? nB : cB + (size_t)(t + 2) * kstep;
;       const char* a3 = a2 + kstep; const char* b3 = b2 + kstep;
;       PG8_LDB(B0, 0, 0); PG8_SCHED; PG8_LDA(At, 0, 0); PG8_STAGE(PG8_SA(1, 1), a1 + hstep, voffA);
;       PG8_WAIT_L(8); PG8_BAR; PG8_WAIT_L(0); PG8_MMA(0, 0, At, B0); PG8_BAR; PG8_SCHED;
;       PG8_LDB(B1, 0, 1); PG8_STAGE(PG8_SB(0, 0), b2, voffB);
;       PG8_BAR; PG8_WAIT_L(0); PG8_MMA(0, 1, At, B1); PG8_BAR;
;       PG8_LDA(At, 0, 1); PG8_STAGE(PG8_SA(0, 0), a2, voffA);
;       PG8_BAR; PG8_WAIT_L(0); PG8_MMA(1, 0, At, B0); PG8_BAR; PG8_SCHED;
;       PG8_STAGE(PG8_SB(0, 1), b2 + hstepB, voffB);
.LBB0_217:
	s_add_i32 s40, s3, 2
	s_add_u32 s18, s16, 0x80
	s_addc_u32 s19, s17, 0
	s_cmp_lg_u32 s39, s3
	s_cselect_b32 s20, s18, 0
	s_cselect_b32 s3, s19, 0
	s_add_u32 s18, s14, s20
	s_addc_u32 s19, s15, s3
	s_add_i32 s41, 16, 0x10000
	v_add_u32_e32 v139, s41, v137
	ds_read_b128 v[140:143], v139
	ds_read_b128 v[148:151], v139 offset:1024
	ds_read_b128 v[152:155], v139 offset:2048
	ds_read_b128 v[156:159], v139 offset:3072
	s_add_u32 s20, s12, s20
	s_addc_u32 s21, s13, s3
	v_lshl_add_u64 v[144:145], v[132:133], 0, s[16:17]
	s_add_i32 m0, s30, 0xc000
	ds_read_b128 v[160:163], v138
	ds_read_b128 v[164:167], v138 offset:1024
	ds_read_b128 v[168:171], v138 offset:2048
	ds_read_b128 v[172:175], v138 offset:3072
	ds_read_b128 v[186:189], v138 offset:4096
	ds_read_b128 v[190:193], v138 offset:5120
	ds_read_b128 v[198:201], v138 offset:6144
	ds_read_b128 v[202:205], v138 offset:7168
	global_load_lds_dwordx4 v[144:145], off
	v_lshl_add_u64 v[144:145], v[134:135], 0, s[16:17]
	s_add_i32 m0, s30, 0xe000
	s_nop 0
	global_load_lds_dwordx4 v[144:145], off
	s_add_i32 s3, 16, 0x14000
	s_add_i32 s41, s41, s29
	v_add_u32_e32 v139, s3, v137
	ds_read_b128 v[206:209], v139
	ds_read_b128 v[214:217], v139 offset:1024
	ds_read_b128 v[218:221], v139 offset:2048
	ds_read_b128 v[222:225], v139 offset:3072
	s_waitcnt lgkmcnt(0)
	s_barrier
	v_mfma_f32_16x16x32_bf16 v[126:129], v[140:143], v[160:163], v[126:129]
	v_mfma_f32_16x16x32_bf16 v[122:125], v[152:155], v[160:163], v[122:125]
	v_mfma_f32_16x16x32_bf16 v[110:113], v[140:143], v[168:171], v[110:113]
	v_mfma_f32_16x16x32_bf16 v[106:109], v[152:155], v[168:171], v[106:109]
	v_mfma_f32_16x16x32_bf16 v[94:97], v[140:143], v[186:189], v[94:97]
	v_mfma_f32_16x16x32_bf16 v[90:93], v[152:155], v[186:189], v[90:93]
	v_mfma_f32_16x16x32_bf16 v[78:81], v[140:143], v[198:201], v[78:81]
	v_mfma_f32_16x16x32_bf16 v[74:77], v[152:155], v[198:201], v[74:77]
	v_mfma_f32_16x16x32_bf16 v[126:129], v[148:151], v[164:167], v[126:129]
	v_mfma_f32_16x16x32_bf16 v[122:125], v[156:159], v[164:167], v[122:125]
	v_mfma_f32_16x16x32_bf16 v[110:113], v[148:151], v[172:175], v[110:113]
	v_mfma_f32_16x16x32_bf16 v[106:109], v[156:159], v[172:175], v[106:109]
	v_mfma_f32_16x16x32_bf16 v[94:97], v[148:151], v[190:193], v[94:97]
	v_mfma_f32_16x16x32_bf16 v[90:93], v[156:159], v[190:193], v[90:93]
	v_mfma_f32_16x16x32_bf16 v[78:81], v[148:151], v[202:205], v[78:81]
	v_mfma_f32_16x16x32_bf16 v[74:77], v[156:159], v[202:205], v[74:77]
	v_mfma_f32_16x16x32_bf16 v[118:121], v[206:209], v[160:163], v[118:121]
	v_mfma_f32_16x16x32_bf16 v[114:117], v[218:221], v[160:163], v[114:117]
	v_mfma_f32_16x16x32_bf16 v[102:105], v[206:209], v[168:171], v[102:105]
	v_mfma_f32_16x16x32_bf16 v[98:101], v[218:221], v[168:171], v[98:101]
	v_mfma_f32_16x16x32_bf16 v[86:89], v[206:209], v[186:189], v[86:89]
	v_mfma_f32_16x16x32_bf16 v[82:85], v[218:221], v[186:189], v[82:85]
	v_mfma_f32_16x16x32_bf16 v[70:73], v[206:209], v[198:201], v[70:73]
	v_mfma_f32_16x16x32_bf16 v[66:69], v[218:221], v[198:201], v[66:69]
	v_mfma_f32_16x16x32_bf16 v[118:121], v[214:217], v[164:167], v[118:121]
	v_mfma_f32_16x16x32_bf16 v[114:117], v[222:225], v[164:167], v[114:117]
	v_mfma_f32_16x16x32_bf16 v[102:105], v[214:217], v[172:175], v[102:105]
	v_mfma_f32_16x16x32_bf16 v[98:101], v[222:225], v[172:175], v[98:101]
	v_mfma_f32_16x16x32_bf16 v[86:89], v[214:217], v[190:193], v[86:89]
	v_mfma_f32_16x16x32_bf16 v[82:85], v[222:225], v[190:193], v[82:85]
	v_mfma_f32_16x16x32_bf16 v[70:73], v[214:217], v[202:205], v[70:73]
	v_mfma_f32_16x16x32_bf16 v[66:69], v[222:225], v[202:205], v[66:69]
	s_mov_b32 m0, s30
	v_lshl_add_u64 v[180:181], s[18:19], 0, v[0:1]
	s_barrier
	ds_read_b128 v[160:163], v138 offset:16384
	ds_read_b128 v[164:167], v138 offset:17408
	ds_read_b128 v[168:171], v138 offset:18432
	ds_read_b128 v[172:175], v138 offset:19456
	ds_read_b128 v[186:189], v138 offset:20480
	ds_read_b128 v[190:193], v138 offset:21504
	ds_read_b128 v[198:201], v138 offset:22528
	ds_read_b128 v[202:205], v138 offset:23552
	global_load_lds_dwordx4 v[180:181], off
	v_lshl_add_u64 v[182:183], s[18:19], 0, v[130:131]
	s_mov_b32 m0, s31
	s_nop 0
	global_load_lds_dwordx4 v[182:183], off
	v_lshl_add_u64 v[230:231], s[20:21], 0, v[0:1]
	s_mov_b32 m0, s41
	s_nop 0
	global_load_lds_dwordx4 v[230:231], off
	v_lshl_add_u64 v[176:177], s[20:21], 0, v[130:131]
	s_add_i32 m0, s41, 0x2000
	s_nop 0
	global_load_lds_dwordx4 v[176:177], off
	s_add_u32 s20, s20, s10
	s_addc_u32 s21, s21, s11
	s_add_i32 s3, s3, s29
	v_lshl_add_u64 v[184:185], s[20:21], 0, v[0:1]
	s_mov_b32 m0, s3
	v_lshl_add_u64 v[226:227], s[20:21], 0, v[130:131]
	global_load_lds_dwordx4 v[184:185], off
	s_add_i32 m0, s3, 0x2000
	s_nop 0
	global_load_lds_dwordx4 v[226:227], off
	s_waitcnt vmcnt(6)
	s_waitcnt lgkmcnt(0)
	s_barrier
; #define PG8_STAGE(bufoff, gbase, voff) do { _Pragma("unroll") for (int _i = 0; _i < 2; ++_i) \
;     __builtin_amdgcn_global_load_lds((const unsigned*)((const char*)(gbase) + (voff)[_i]), (LAS unsigned*)(lds + (bufoff) + ldsw + _i * 8192), 16, 0, 0); } while (0)
; #define PG8_LDA(dst, b, h) do { _Pragma("unroll") for (int m = 0; m < 4; ++m) _Pragma("unroll") for (int k = 0; k < 2; ++k) dst[m][k] = *(const LAS bf16x8*)(lds + PG8_SA(b, h) + aoff + m * 2048 + k * 1024); } while (0)
; #define PG8_LDB(dst, b, h) do { _Pragma("unroll") for (int n = 0; n < 2; ++n) _Pragma("unroll") for (int k = 0; k < 2; ++k) dst[n][k] = *(const LAS bf16x8*)(lds + PG8_SB(b, h) + boff + n * 2048 + k * 1024); } while (0)
; #define PG8_MMA(ai, bj, At, Bt) do { __builtin_amdgcn_s_setprio(1); _Pragma("unroll") for (int m = 0; m < 4; ++m) _Pragma("unroll") for (int n = 0; n < 2; ++n) _Pragma("unroll") for (int k = 0; k < 2; ++k) \
;     acc[ai][bj][m][n] = __builtin_amdgcn_mfma_f32_16x16x32_bf16(Bt[n][k], At[m][k], acc[ai][bj][m][n], 0, 0, 0); __builtin_amdgcn_s_setprio(0); } while (0)
; #define PG8_WAIT_V(n) asm volatile("s_waitcnt vmcnt(" #n ")" ::: "memory")
; #define PG8_WAIT_L(n) asm volatile("s_waitcnt lgkmcnt(" #n ")" ::: "memory")
; #define PG8_BAR __builtin_amdgcn_s_barrier()
; #define PG8_SCHED __builtin_amdgcn_sched_barrier(0)
; template <class Epi, class Sched>
; DI void gemm_phase(LAS unsigned char* lds, const Gemm g, const Sched& S, const Epi& E) {
;     ...
;       PG8_BAR; PG8_WAIT_L(0); PG8_MMA(1, 0, At, B0); PG8_BAR; PG8_SCHED;
;       PG8_STAGE(PG8_SB(0, 1), b2 + hstepB, voffB);
;       PG8_WAIT_V(6); PG8_BAR; PG8_MMA(1, 1, At, B1); PG8_BAR;
;       PG8_LDB(B0, 1, 0); PG8_SCHED; PG8_LDA(At, 1, 0); PG8_STAGE(PG8_SA(0, 1), a2 + hstep, voffA);
;       PG8_WAIT_L(8); PG8_BAR; PG8_WAIT_L(0); PG8_MMA(0, 0, At, B0); PG8_BAR; PG8_SCHED;
;       PG8_LDB(B1, 1, 1); PG8_STAGE(PG8_SB(1, 0), b3, voffB);
;       PG8_BAR; PG8_WAIT_L(0); PG8_MMA(0, 1, At, B1); PG8_BAR;
	v_mfma_f32_16x16x32_bf16 v[62:65], v[140:143], v[160:163], v[62:65]
	v_mfma_f32_16x16x32_bf16 v[58:61], v[152:155], v[160:163], v[58:61]
	v_mfma_f32_16x16x32_bf16 v[50:53], v[140:143], v[168:171], v[50:53]
	v_mfma_f32_16x16x32_bf16 v[42:45], v[152:155], v[168:171], v[42:45]
	v_mfma_f32_16x16x32_bf16 v[34:37], v[140:143], v[186:189], v[34:37]
	v_mfma_f32_16x16x32_bf16 v[26:29], v[152:155], v[186:189], v[26:29]
	v_mfma_f32_16x16x32_bf16 v[14:17], v[140:143], v[198:201], v[14:17]
	v_mfma_f32_16x16x32_bf16 v[10:13], v[152:155], v[198:201], v[10:13]
	v_mfma_f32_16x16x32_bf16 v[62:65], v[148:151], v[164:167], v[62:65]
	v_mfma_f32_16x16x32_bf16 v[58:61], v[156:159], v[164:167], v[58:61]
	v_mfma_f32_16x16x32_bf16 v[50:53], v[148:151], v[172:175], v[50:53]
	v_mfma_f32_16x16x32_bf16 v[42:45], v[156:159], v[172:175], v[42:45]
	v_mfma_f32_16x16x32_bf16 v[34:37], v[148:151], v[190:193], v[34:37]
	v_mfma_f32_16x16x32_bf16 v[26:29], v[156:159], v[190:193], v[26:29]
	v_mfma_f32_16x16x32_bf16 v[14:17], v[148:151], v[202:205], v[14:17]
	v_mfma_f32_16x16x32_bf16 v[10:13], v[156:159], v[202:205], v[10:13]
	v_mfma_f32_16x16x32_bf16 v[54:57], v[206:209], v[160:163], v[54:57]
	v_mfma_f32_16x16x32_bf16 v[46:49], v[218:221], v[160:163], v[46:49]
	v_mfma_f32_16x16x32_bf16 v[38:41], v[206:209], v[168:171], v[38:41]
	v_mfma_f32_16x16x32_bf16 v[30:33], v[218:221], v[168:171], v[30:33]
	v_mfma_f32_16x16x32_bf16 v[22:25], v[206:209], v[186:189], v[22:25]
	v_mfma_f32_16x16x32_bf16 v[18:21], v[218:221], v[186:189], v[18:21]
	v_mfma_f32_16x16x32_bf16 v[6:9], v[206:209], v[198:201], v[6:9]
	v_mfma_f32_16x16x32_bf16 v[2:5], v[218:221], v[198:201], v[2:5]
	v_mfma_f32_16x16x32_bf16 v[54:57], v[214:217], v[164:167], v[54:57]
	v_mfma_f32_16x16x32_bf16 v[46:49], v[222:225], v[164:167], v[46:49]
	v_mfma_f32_16x16x32_bf16 v[38:41], v[214:217], v[172:175], v[38:41]
	v_mfma_f32_16x16x32_bf16 v[30:33], v[222:225], v[172:175], v[30:33]
	v_mfma_f32_16x16x32_bf16 v[22:25], v[214:217], v[190:193], v[22:25]
	v_mfma_f32_16x16x32_bf16 v[18:21], v[222:225], v[190:193], v[18:21]
	v_mfma_f32_16x16x32_bf16 v[6:9], v[214:217], v[202:205], v[6:9]
	v_mfma_f32_16x16x32_bf16 v[2:5], v[222:225], v[202:205], v[2:5]
	s_add_i32 s3, 16, 0x18000
	v_add_u32_e32 v139, s3, v137
	s_barrier
	ds_read_b128 v[140:143], v139
	ds_read_b128 v[148:151], v139 offset:1024
	ds_read_b128 v[152:155], v139 offset:2048
	ds_read_b128 v[156:159], v139 offset:3072
	s_add_u32 s18, s18, s10
	s_addc_u32 s19, s19, s11
	s_mov_b32 m0, s34
	v_lshl_add_u64 v[206:207], s[18:19], 0, v[0:1]
	ds_read_b128 v[160:163], v138 offset:32768
	ds_read_b128 v[164:167], v138 offset:33792
	ds_read_b128 v[168:171], v138 offset:34816
	ds_read_b128 v[172:175], v138 offset:35840
	ds_read_b128 v[186:189], v138 offset:36864
	ds_read_b128 v[190:193], v138 offset:37888
	ds_read_b128 v[198:201], v138 offset:38912
	ds_read_b128 v[202:205], v138 offset:39936
	global_load_lds_dwordx4 v[206:207], off
	v_lshl_add_u64 v[206:207], s[18:19], 0, v[130:131]
	s_mov_b32 m0, s35
	s_nop 0
	global_load_lds_dwordx4 v[206:207], off
	s_add_i32 s18, 16, 0x1c000
	s_add_i32 s3, s3, s29
	v_add_u32_e32 v139, s18, v137
	ds_read_b128 v[206:209], v139
	ds_read_b128 v[214:217], v139 offset:1024
	ds_read_b128 v[218:221], v139 offset:2048
	ds_read_b128 v[222:225], v139 offset:3072
	s_waitcnt lgkmcnt(0)
	s_barrier
	v_mfma_f32_16x16x32_bf16 v[126:129], v[140:143], v[160:163], v[126:129]
	v_mfma_f32_16x16x32_bf16 v[122:125], v[152:155], v[160:163], v[122:125]
	v_mfma_f32_16x16x32_bf16 v[110:113], v[140:143], v[168:171], v[110:113]
	v_mfma_f32_16x16x32_bf16 v[106:109], v[152:155], v[168:171], v[106:109]
	v_mfma_f32_16x16x32_bf16 v[94:97], v[140:143], v[186:189], v[94:97]
	v_mfma_f32_16x16x32_bf16 v[90:93], v[152:155], v[186:189], v[90:93]
	v_mfma_f32_16x16x32_bf16 v[78:81], v[140:143], v[198:201], v[78:81]
	v_mfma_f32_16x16x32_bf16 v[74:77], v[152:155], v[198:201], v[74:77]
	v_mfma_f32_16x16x32_bf16 v[126:129], v[148:151], v[164:167], v[126:129]
	v_mfma_f32_16x16x32_bf16 v[122:125], v[156:159], v[164:167], v[122:125]
	v_mfma_f32_16x16x32_bf16 v[110:113], v[148:151], v[172:175], v[110:113]
	v_mfma_f32_16x16x32_bf16 v[106:109], v[156:159], v[172:175], v[106:109]
	v_mfma_f32_16x16x32_bf16 v[94:97], v[148:151], v[190:193], v[94:97]
	v_mfma_f32_16x16x32_bf16 v[90:93], v[156:159], v[190:193], v[90:93]
	v_mfma_f32_16x16x32_bf16 v[78:81], v[148:151], v[202:205], v[78:81]
	v_mfma_f32_16x16x32_bf16 v[74:77], v[156:159], v[202:205], v[74:77]
	v_mfma_f32_16x16x32_bf16 v[118:121], v[206:209], v[160:163], v[118:121]
	v_mfma_f32_16x16x32_bf16 v[114:117], v[218:221], v[160:163], v[114:117]
	v_mfma_f32_16x16x32_bf16 v[102:105], v[206:209], v[168:171], v[102:105]
	v_mfma_f32_16x16x32_bf16 v[98:101], v[218:221], v[168:171], v[98:101]
	v_mfma_f32_16x16x32_bf16 v[86:89], v[206:209], v[186:189], v[86:89]
	v_mfma_f32_16x16x32_bf16 v[82:85], v[218:221], v[186:189], v[82:85]
	v_mfma_f32_16x16x32_bf16 v[70:73], v[206:209], v[198:201], v[70:73]
	v_mfma_f32_16x16x32_bf16 v[66:69], v[218:221], v[198:201], v[66:69]
	v_mfma_f32_16x16x32_bf16 v[118:121], v[214:217], v[164:167], v[118:121]
	v_mfma_f32_16x16x32_bf16 v[114:117], v[222:225], v[164:167], v[114:117]
	v_mfma_f32_16x16x32_bf16 v[102:105], v[214:217], v[172:175], v[102:105]
	v_mfma_f32_16x16x32_bf16 v[98:101], v[222:225], v[172:175], v[98:101]
	v_mfma_f32_16x16x32_bf16 v[86:89], v[214:217], v[190:193], v[86:89]
	v_mfma_f32_16x16x32_bf16 v[82:85], v[222:225], v[190:193], v[82:85]
	v_mfma_f32_16x16x32_bf16 v[70:73], v[214:217], v[202:205], v[70:73]
	v_mfma_f32_16x16x32_bf16 v[66:69], v[222:225], v[202:205], v[66:69]
	s_mov_b32 m0, s36
	v_lshl_add_u64 v[144:145], v[180:181], 0, s[70:71]
	s_barrier
; #define PG8_STAGE(bufoff, gbase, voff) do { _Pragma("unroll") for (int _i = 0; _i < 2; ++_i) \
;     __builtin_amdgcn_global_load_lds((const unsigned*)((const char*)(gbase) + (voff)[_i]), (LAS unsigned*)(lds + (bufoff) + ldsw + _i * 8192), 16, 0, 0); } while (0)
; #define PG8_LDA(dst, b, h) do { _Pragma("unroll") for (int m = 0; m < 4; ++m) _Pragma("unroll") for (int k = 0; k < 2; ++k) dst[m][k] = *(const LAS bf16x8*)(lds + PG8_SA(b, h) + aoff + m * 2048 + k * 1024); } while (0)
; #define PG8_MMA(ai, bj, At, Bt) do { __builtin_amdgcn_s_setprio(1); _Pragma("unroll") for (int m = 0; m < 4; ++m) _Pragma("unroll") for (int n = 0; n < 2; ++n) _Pragma("unroll") for (int k = 0; k < 2; ++k) \
;     acc[ai][bj][m][n] = __builtin_amdgcn_mfma_f32_16x16x32_bf16(Bt[n][k], At[m][k], acc[ai][bj][m][n], 0, 0, 0); __builtin_amdgcn_s_setprio(0); } while (0)
; #define PG8_WAIT_V(n) asm volatile("s_waitcnt vmcnt(" #n ")" ::: "memory")
; #define PG8_WAIT_L(n) asm volatile("s_waitcnt lgkmcnt(" #n ")" ::: "memory")
; #define PG8_BAR __builtin_amdgcn_s_barrier()
; #define PG8_SCHED __builtin_amdgcn_sched_barrier(0)
; template <class Epi, class Sched>
; DI void gemm_phase(LAS unsigned char* lds, const Gemm g, const Sched& S, const Epi& E) {
;     ...
;       PG8_LDA(At, 1, 1); PG8_STAGE(PG8_SA(1, 0), a3, voffA);
;       PG8_BAR; PG8_WAIT_L(0); PG8_MMA(1, 0, At, B0); PG8_BAR; PG8_SCHED;
;       PG8_STAGE(PG8_SB(1, 1), b3 + hstepB, voffB);
;       PG8_WAIT_V(6); PG8_BAR; PG8_MMA(1, 1, At, B1); PG8_BAR;
	ds_read_b128 v[160:163], v138 offset:49152
	ds_read_b128 v[164:167], v138 offset:50176
	ds_read_b128 v[168:171], v138 offset:51200
	ds_read_b128 v[172:175], v138 offset:52224
	ds_read_b128 v[186:189], v138 offset:53248
	ds_read_b128 v[190:193], v138 offset:54272
	ds_read_b128 v[198:201], v138 offset:55296
	ds_read_b128 v[202:205], v138 offset:56320
	global_load_lds_dwordx4 v[144:145], off
	v_lshl_add_u64 v[144:145], v[182:183], 0, s[70:71]
	s_mov_b32 m0, s37
	s_nop 0
	global_load_lds_dwordx4 v[144:145], off
	v_lshl_add_u64 v[230:231], v[230:231], 0, s[70:71]
	s_mov_b32 m0, s3
	s_nop 0
	global_load_lds_dwordx4 v[230:231], off
	v_lshl_add_u64 v[144:145], v[176:177], 0, s[70:71]
	s_add_i32 m0, s3, 0x2000
	s_nop 0
	global_load_lds_dwordx4 v[144:145], off
	s_add_i32 s3, s18, s29
	v_lshl_add_u64 v[232:233], v[184:185], 0, s[70:71]
	s_mov_b32 m0, s3
	s_nop 0
	global_load_lds_dwordx4 v[232:233], off
	v_lshl_add_u64 v[232:233], v[226:227], 0, s[70:71]
	s_add_i32 m0, s3, 0x2000
	s_nop 0
	global_load_lds_dwordx4 v[232:233], off
	s_waitcnt vmcnt(6)
	s_waitcnt lgkmcnt(0)
	s_barrier
	v_mfma_f32_16x16x32_bf16 v[62:65], v[140:143], v[160:163], v[62:65]
	v_mfma_f32_16x16x32_bf16 v[58:61], v[152:155], v[160:163], v[58:61]
	v_mfma_f32_16x16x32_bf16 v[50:53], v[140:143], v[168:171], v[50:53]
	v_mfma_f32_16x16x32_bf16 v[42:45], v[152:155], v[168:171], v[42:45]
	v_mfma_f32_16x16x32_bf16 v[34:37], v[140:143], v[186:189], v[34:37]
	v_mfma_f32_16x16x32_bf16 v[26:29], v[152:155], v[186:189], v[26:29]
	v_mfma_f32_16x16x32_bf16 v[14:17], v[140:143], v[198:201], v[14:17]
	v_mfma_f32_16x16x32_bf16 v[10:13], v[152:155], v[198:201], v[10:13]
	v_mfma_f32_16x16x32_bf16 v[62:65], v[148:151], v[164:167], v[62:65]
	v_mfma_f32_16x16x32_bf16 v[58:61], v[156:159], v[164:167], v[58:61]
	v_mfma_f32_16x16x32_bf16 v[50:53], v[148:151], v[172:175], v[50:53]
	v_mfma_f32_16x16x32_bf16 v[42:45], v[156:159], v[172:175], v[42:45]
	v_mfma_f32_16x16x32_bf16 v[34:37], v[148:151], v[190:193], v[34:37]
	v_mfma_f32_16x16x32_bf16 v[26:29], v[156:159], v[190:193], v[26:29]
	v_mfma_f32_16x16x32_bf16 v[14:17], v[148:151], v[202:205], v[14:17]
	v_mfma_f32_16x16x32_bf16 v[10:13], v[156:159], v[202:205], v[10:13]
	v_mfma_f32_16x16x32_bf16 v[54:57], v[206:209], v[160:163], v[54:57]
	v_mfma_f32_16x16x32_bf16 v[46:49], v[218:221], v[160:163], v[46:49]
	v_mfma_f32_16x16x32_bf16 v[38:41], v[206:209], v[168:171], v[38:41]
	v_mfma_f32_16x16x32_bf16 v[30:33], v[218:221], v[168:171], v[30:33]
	v_mfma_f32_16x16x32_bf16 v[22:25], v[206:209], v[186:189], v[22:25]
	v_mfma_f32_16x16x32_bf16 v[18:21], v[218:221], v[186:189], v[18:21]
	v_mfma_f32_16x16x32_bf16 v[6:9], v[206:209], v[198:201], v[6:9]
	v_mfma_f32_16x16x32_bf16 v[2:5], v[218:221], v[198:201], v[2:5]
	v_mfma_f32_16x16x32_bf16 v[54:57], v[214:217], v[164:167], v[54:57]
	v_mfma_f32_16x16x32_bf16 v[46:49], v[222:225], v[164:167], v[46:49]
	v_mfma_f32_16x16x32_bf16 v[38:41], v[214:217], v[172:175], v[38:41]
	v_mfma_f32_16x16x32_bf16 v[30:33], v[222:225], v[172:175], v[30:33]
	v_mfma_f32_16x16x32_bf16 v[22:25], v[214:217], v[190:193], v[22:25]
	v_mfma_f32_16x16x32_bf16 v[18:21], v[222:225], v[190:193], v[18:21]
	v_mfma_f32_16x16x32_bf16 v[6:9], v[214:217], v[202:205], v[6:9]
	v_mfma_f32_16x16x32_bf16 v[2:5], v[222:225], v[202:205], v[2:5]
	s_add_u32 s16, s16, 0x100
	s_addc_u32 s17, s17, 0
	s_cmp_ge_i32 s40, s38
	s_mov_b32 s3, s40
	s_barrier
	s_cbranch_scc0 .LBB0_217

; #define PG8_STAGE(bufoff, gbase, voff) do { _Pragma("unroll") for (int _i = 0; _i < 2; ++_i) \
;     __builtin_amdgcn_global_load_lds((const unsigned*)((const char*)(gbase) + (voff)[_i]), (LAS unsigned*)(lds + (bufoff) + ldsw + _i * 8192), 16, 0, 0); } while (0)
; #define PG8_LDA(dst, b, h) do { _Pragma("unroll") for (int m = 0; m < 4; ++m) _Pragma("unroll") for (int k = 0; k < 2; ++k) dst[m][k] = *(const LAS bf16x8*)(lds + PG8_SA(b, h) + aoff + m * 2048 + k * 1024); } while (0)
; #define PG8_LDB(dst, b, h) do { _Pragma("unroll") for (int n = 0; n < 2; ++n) _Pragma("unroll") for (int k = 0; k < 2; ++k) dst[n][k] = *(const LAS bf16x8*)(lds + PG8_SB(b, h) + boff + n * 2048 + k * 1024); } while (0)
; #define PG8_MMA(ai, bj, At, Bt) do { __builtin_amdgcn_s_setprio(1); _Pragma("unroll") for (int m = 0; m < 4; ++m) _Pragma("unroll") for (int n = 0; n < 2; ++n) _Pragma("unroll") for (int k = 0; k < 2; ++k) \
;     acc[ai][bj][m][n] = __builtin_amdgcn_mfma_f32_16x16x32_bf16(Bt[n][k], At[m][k], acc[ai][bj][m][n], 0, 0, 0); __builtin_amdgcn_s_setprio(0); } while (0)
; #define PG8_WAIT_L(n) asm volatile("s_waitcnt lgkmcnt(" #n ")" ::: "memory")
; #define PG8_BAR __builtin_amdgcn_s_barrier()
; #define PG8_SCHED __builtin_amdgcn_sched_barrier(0)
; template <class Epi, class Sched>
; DI void gemm_phase(LAS unsigned char* lds, const Gemm g, const Sched& S, const Epi& E) {
;     ...
;     for (int t = 0; t < nt; t += 2) {
;       const bool last = (t == nt - 2);
;       const char* a1 = cA + (size_t)(t + 1) * kstep;
;       const char* a2 = last ? nA : cA + (size_t)(t + 2) * kstep; const char* b2 = last ? nB : cB + (size_t)(t + 2) * kstep;
;       const char* a3 = a2 + kstep; const char* b3 = b2 + kstep;
;       PG8_LDB(B0, 0, 0); PG8_SCHED; PG8_LDA(At, 0, 0); PG8_STAGE(PG8_SA(1, 1), a1 + hstep, voffA);
;       PG8_WAIT_L(8); PG8_BAR; PG8_WAIT_L(0); PG8_MMA(0, 0, At, B0); PG8_BAR; PG8_SCHED;
;       PG8_LDB(B1, 0, 1); PG8_STAGE(PG8_SB(0, 0), b2, voffB);
;       PG8_BAR; PG8_WAIT_L(0); PG8_MMA(0, 1, At, B1); PG8_BAR;
;       PG8_LDA(At, 0, 1); PG8_STAGE(PG8_SA(0, 0), a2, voffA);
;       PG8_BAR; PG8_WAIT_L(0); PG8_MMA(1, 0, At, B0); PG8_BAR; PG8_SCHED;
;       PG8_STAGE(PG8_SB(0, 1), b2 + hstepB, voffB);
.LBB0_491:
	s_add_i32 s26, s8, 2
	s_add_u32 s9, s6, 0xfe000080
	s_addc_u32 s10, s7, -1
	s_cmp_lg_u32 s25, s8
	s_cselect_b32 s11, s10, 0
	s_cselect_b32 s10, s9, 0
	s_add_u32 s8, s4, s10
	s_addc_u32 s9, s5, s11
	s_add_i32 s27, 16, 0x10000
	v_add_u32_e32 v139, s27, v133
	ds_read_b128 v[140:143], v139
	ds_read_b128 v[148:151], v139 offset:1024
	ds_read_b128 v[152:155], v139 offset:2048
	ds_read_b128 v[156:159], v139 offset:3072
	s_add_u32 s10, s2, s10
	s_addc_u32 s11, s3, s11
	v_lshl_add_u64 v[144:145], v[128:129], 0, s[6:7]
	s_add_i32 m0, s18, 0xc000
	ds_read_b128 v[160:163], v138
	ds_read_b128 v[164:167], v138 offset:1024
	ds_read_b128 v[168:171], v138 offset:2048
	ds_read_b128 v[172:175], v138 offset:3072
	ds_read_b128 v[186:189], v138 offset:4096
	ds_read_b128 v[190:193], v138 offset:5120
	ds_read_b128 v[198:201], v138 offset:6144
	ds_read_b128 v[202:205], v138 offset:7168
	global_load_lds_dwordx4 v[144:145], off
	v_lshl_add_u64 v[144:145], v[130:131], 0, s[6:7]
	s_add_i32 m0, s18, 0xe000
	s_nop 0
	global_load_lds_dwordx4 v[144:145], off
	s_add_i32 s28, 16, 0x14000
	s_add_i32 s27, s27, s17
	v_add_u32_e32 v139, s28, v133
	ds_read_b128 v[206:209], v139
	ds_read_b128 v[214:217], v139 offset:1024
	ds_read_b128 v[218:221], v139 offset:2048
	ds_read_b128 v[222:225], v139 offset:3072
	s_waitcnt lgkmcnt(0)
	s_barrier
	v_mfma_f32_16x16x32_bf16 v[134:137], v[140:143], v[160:163], v[134:137]
	v_mfma_f32_16x16x32_bf16 v[122:125], v[152:155], v[160:163], v[122:125]
	v_mfma_f32_16x16x32_bf16 v[110:113], v[140:143], v[168:171], v[110:113]
	v_mfma_f32_16x16x32_bf16 v[106:109], v[152:155], v[168:171], v[106:109]
	v_mfma_f32_16x16x32_bf16 v[94:97], v[140:143], v[186:189], v[94:97]
	v_mfma_f32_16x16x32_bf16 v[90:93], v[152:155], v[186:189], v[90:93]
	v_mfma_f32_16x16x32_bf16 v[78:81], v[140:143], v[198:201], v[78:81]
	v_mfma_f32_16x16x32_bf16 v[74:77], v[152:155], v[198:201], v[74:77]
	v_mfma_f32_16x16x32_bf16 v[134:137], v[148:151], v[164:167], v[134:137]
	v_mfma_f32_16x16x32_bf16 v[122:125], v[156:159], v[164:167], v[122:125]
	v_mfma_f32_16x16x32_bf16 v[110:113], v[148:151], v[172:175], v[110:113]
	v_mfma_f32_16x16x32_bf16 v[106:109], v[156:159], v[172:175], v[106:109]
	v_mfma_f32_16x16x32_bf16 v[94:97], v[148:151], v[190:193], v[94:97]
	v_mfma_f32_16x16x32_bf16 v[90:93], v[156:159], v[190:193], v[90:93]
	v_mfma_f32_16x16x32_bf16 v[78:81], v[148:151], v[202:205], v[78:81]
	v_mfma_f32_16x16x32_bf16 v[74:77], v[156:159], v[202:205], v[74:77]
	v_mfma_f32_16x16x32_bf16 v[118:121], v[206:209], v[160:163], v[118:121]
	v_mfma_f32_16x16x32_bf16 v[114:117], v[218:221], v[160:163], v[114:117]
	v_mfma_f32_16x16x32_bf16 v[102:105], v[206:209], v[168:171], v[102:105]
	v_mfma_f32_16x16x32_bf16 v[98:101], v[218:221], v[168:171], v[98:101]
	v_mfma_f32_16x16x32_bf16 v[86:89], v[206:209], v[186:189], v[86:89]
	v_mfma_f32_16x16x32_bf16 v[82:85], v[218:221], v[186:189], v[82:85]
	v_mfma_f32_16x16x32_bf16 v[70:73], v[206:209], v[198:201], v[70:73]
	v_mfma_f32_16x16x32_bf16 v[66:69], v[218:221], v[198:201], v[66:69]
	v_mfma_f32_16x16x32_bf16 v[118:121], v[214:217], v[164:167], v[118:121]
	v_mfma_f32_16x16x32_bf16 v[114:117], v[222:225], v[164:167], v[114:117]
	v_mfma_f32_16x16x32_bf16 v[102:105], v[214:217], v[172:175], v[102:105]
	v_mfma_f32_16x16x32_bf16 v[98:101], v[222:225], v[172:175], v[98:101]
	v_mfma_f32_16x16x32_bf16 v[86:89], v[214:217], v[190:193], v[86:89]
	v_mfma_f32_16x16x32_bf16 v[82:85], v[222:225], v[190:193], v[82:85]
	v_mfma_f32_16x16x32_bf16 v[70:73], v[214:217], v[202:205], v[70:73]
	v_mfma_f32_16x16x32_bf16 v[66:69], v[222:225], v[202:205], v[66:69]
	s_mov_b32 m0, s18
	v_lshl_add_u64 v[180:181], s[8:9], 0, v[0:1]
	s_barrier
	ds_read_b128 v[160:163], v138 offset:16384
	ds_read_b128 v[164:167], v138 offset:17408
	ds_read_b128 v[168:171], v138 offset:18432
	ds_read_b128 v[172:175], v138 offset:19456
	ds_read_b128 v[186:189], v138 offset:20480
	ds_read_b128 v[190:193], v138 offset:21504
	ds_read_b128 v[198:201], v138 offset:22528
	ds_read_b128 v[202:205], v138 offset:23552
	global_load_lds_dwordx4 v[180:181], off
	v_lshl_add_u64 v[182:183], s[8:9], 0, v[126:127]
	s_mov_b32 m0, s19
	s_nop 0
	global_load_lds_dwordx4 v[182:183], off
	v_lshl_add_u64 v[230:231], s[10:11], 0, v[0:1]
	s_mov_b32 m0, s27
	s_nop 0
	global_load_lds_dwordx4 v[230:231], off
	v_lshl_add_u64 v[176:177], s[10:11], 0, v[126:127]
	s_add_i32 m0, s27, 0x2000
	s_nop 0
	global_load_lds_dwordx4 v[176:177], off
	s_add_u32 s10, s10, s0
	s_addc_u32 s11, s11, s1
	s_add_i32 s27, s28, s17
	v_lshl_add_u64 v[184:185], s[10:11], 0, v[0:1]
	s_mov_b32 m0, s27
	v_lshl_add_u64 v[226:227], s[10:11], 0, v[126:127]
	global_load_lds_dwordx4 v[184:185], off
	s_add_i32 m0, s27, 0x2000
	s_nop 0
	global_load_lds_dwordx4 v[226:227], off
	s_waitcnt vmcnt(6)
	s_waitcnt lgkmcnt(0)
	s_barrier
; #define PG8_STAGE(bufoff, gbase, voff) do { _Pragma("unroll") for (int _i = 0; _i < 2; ++_i) \
;     __builtin_amdgcn_global_load_lds((const unsigned*)((const char*)(gbase) + (voff)[_i]), (LAS unsigned*)(lds + (bufoff) + ldsw + _i * 8192), 16, 0, 0); } while (0)
; #define PG8_LDA(dst, b, h) do { _Pragma("unroll") for (int m = 0; m < 4; ++m) _Pragma("unroll") for (int k = 0; k < 2; ++k) dst[m][k] = *(const LAS bf16x8*)(lds + PG8_SA(b, h) + aoff + m * 2048 + k * 1024); } while (0)
; #define PG8_LDB(dst, b, h) do { _Pragma("unroll") for (int n = 0; n < 2; ++n) _Pragma("unroll") for (int k = 0; k < 2; ++k) dst[n][k] = *(const LAS bf16x8*)(lds + PG8_SB(b, h) + boff + n * 2048 + k * 1024); } while (0)
; #define PG8_MMA(ai, bj, At, Bt) do { __builtin_amdgcn_s_setprio(1); _Pragma("unroll") for (int m = 0; m < 4; ++m) _Pragma("unroll") for (int n = 0; n < 2; ++n) _Pragma("unroll") for (int k = 0; k < 2; ++k) \
;     acc[ai][bj][m][n] = __builtin_amdgcn_mfma_f32_16x16x32_bf16(Bt[n][k], At[m][k], acc[ai][bj][m][n], 0, 0, 0); __builtin_amdgcn_s_setprio(0); } while (0)
; #define PG8_WAIT_V(n) asm volatile("s_waitcnt vmcnt(" #n ")" ::: "memory")
; #define PG8_WAIT_L(n) asm volatile("s_waitcnt lgkmcnt(" #n ")" ::: "memory")
; #define PG8_BAR __builtin_amdgcn_s_barrier()
; #define PG8_SCHED __builtin_amdgcn_sched_barrier(0)
; template <class Epi, class Sched>
; DI void gemm_phase(LAS unsigned char* lds, const Gemm g, const Sched& S, const Epi& E) {
;     ...
;       PG8_BAR; PG8_WAIT_L(0); PG8_MMA(1, 0, At, B0); PG8_BAR; PG8_SCHED;
;       PG8_STAGE(PG8_SB(0, 1), b2 + hstepB, voffB);
;       PG8_WAIT_V(6); PG8_BAR; PG8_MMA(1, 1, At, B1); PG8_BAR;
;       PG8_LDB(B0, 1, 0); PG8_SCHED; PG8_LDA(At, 1, 0); PG8_STAGE(PG8_SA(0, 1), a2 + hstep, voffA);
;       PG8_WAIT_L(8); PG8_BAR; PG8_WAIT_L(0); PG8_MMA(0, 0, At, B0); PG8_BAR; PG8_SCHED;
;       PG8_LDB(B1, 1, 1); PG8_STAGE(PG8_SB(1, 0), b3, voffB);
;       PG8_BAR; PG8_WAIT_L(0); PG8_MMA(0, 1, At, B1); PG8_BAR;
	v_mfma_f32_16x16x32_bf16 v[62:65], v[140:143], v[160:163], v[62:65]
	v_mfma_f32_16x16x32_bf16 v[58:61], v[152:155], v[160:163], v[58:61]
	v_mfma_f32_16x16x32_bf16 v[50:53], v[140:143], v[168:171], v[50:53]
	v_mfma_f32_16x16x32_bf16 v[42:45], v[152:155], v[168:171], v[42:45]
	v_mfma_f32_16x16x32_bf16 v[34:37], v[140:143], v[186:189], v[34:37]
	v_mfma_f32_16x16x32_bf16 v[26:29], v[152:155], v[186:189], v[26:29]
	v_mfma_f32_16x16x32_bf16 v[18:21], v[140:143], v[198:201], v[18:21]
	v_mfma_f32_16x16x32_bf16 v[10:13], v[152:155], v[198:201], v[10:13]
	v_mfma_f32_16x16x32_bf16 v[62:65], v[148:151], v[164:167], v[62:65]
	v_mfma_f32_16x16x32_bf16 v[58:61], v[156:159], v[164:167], v[58:61]
	v_mfma_f32_16x16x32_bf16 v[50:53], v[148:151], v[172:175], v[50:53]
	v_mfma_f32_16x16x32_bf16 v[42:45], v[156:159], v[172:175], v[42:45]
	v_mfma_f32_16x16x32_bf16 v[34:37], v[148:151], v[190:193], v[34:37]
	v_mfma_f32_16x16x32_bf16 v[26:29], v[156:159], v[190:193], v[26:29]
	v_mfma_f32_16x16x32_bf16 v[18:21], v[148:151], v[202:205], v[18:21]
	v_mfma_f32_16x16x32_bf16 v[10:13], v[156:159], v[202:205], v[10:13]
	v_mfma_f32_16x16x32_bf16 v[54:57], v[206:209], v[160:163], v[54:57]
	v_mfma_f32_16x16x32_bf16 v[46:49], v[218:221], v[160:163], v[46:49]
	v_mfma_f32_16x16x32_bf16 v[38:41], v[206:209], v[168:171], v[38:41]
	v_mfma_f32_16x16x32_bf16 v[30:33], v[218:221], v[168:171], v[30:33]
	v_mfma_f32_16x16x32_bf16 v[22:25], v[206:209], v[186:189], v[22:25]
	v_mfma_f32_16x16x32_bf16 v[14:17], v[218:221], v[186:189], v[14:17]
	v_mfma_f32_16x16x32_bf16 v[6:9], v[206:209], v[198:201], v[6:9]
	v_mfma_f32_16x16x32_bf16 v[2:5], v[218:221], v[198:201], v[2:5]
	v_mfma_f32_16x16x32_bf16 v[54:57], v[214:217], v[164:167], v[54:57]
	v_mfma_f32_16x16x32_bf16 v[46:49], v[222:225], v[164:167], v[46:49]
	v_mfma_f32_16x16x32_bf16 v[38:41], v[214:217], v[172:175], v[38:41]
	v_mfma_f32_16x16x32_bf16 v[30:33], v[222:225], v[172:175], v[30:33]
	v_mfma_f32_16x16x32_bf16 v[22:25], v[214:217], v[190:193], v[22:25]
	v_mfma_f32_16x16x32_bf16 v[14:17], v[222:225], v[190:193], v[14:17]
	v_mfma_f32_16x16x32_bf16 v[6:9], v[214:217], v[202:205], v[6:9]
	v_mfma_f32_16x16x32_bf16 v[2:5], v[222:225], v[202:205], v[2:5]
	s_add_i32 s10, 16, 0x18000
	v_add_u32_e32 v139, s10, v133
	s_barrier
	ds_read_b128 v[140:143], v139
	ds_read_b128 v[148:151], v139 offset:1024
	ds_read_b128 v[152:155], v139 offset:2048
	ds_read_b128 v[156:159], v139 offset:3072
	s_add_u32 s8, s8, s0
	s_addc_u32 s9, s9, s1
	s_mov_b32 m0, s20
	v_lshl_add_u64 v[206:207], s[8:9], 0, v[0:1]
	ds_read_b128 v[160:163], v138 offset:32768
	ds_read_b128 v[164:167], v138 offset:33792
	ds_read_b128 v[168:171], v138 offset:34816
	ds_read_b128 v[172:175], v138 offset:35840
	ds_read_b128 v[186:189], v138 offset:36864
	ds_read_b128 v[190:193], v138 offset:37888
	ds_read_b128 v[198:201], v138 offset:38912
	ds_read_b128 v[202:205], v138 offset:39936
	global_load_lds_dwordx4 v[206:207], off
	v_lshl_add_u64 v[206:207], s[8:9], 0, v[126:127]
	s_mov_b32 m0, s21
	s_nop 0
	global_load_lds_dwordx4 v[206:207], off
	s_add_i32 s8, 16, 0x1c000
	s_add_i32 s9, s10, s17
	v_add_u32_e32 v139, s8, v133
	ds_read_b128 v[206:209], v139
	ds_read_b128 v[214:217], v139 offset:1024
	ds_read_b128 v[218:221], v139 offset:2048
	ds_read_b128 v[222:225], v139 offset:3072
	s_waitcnt lgkmcnt(0)
	s_barrier
	v_mfma_f32_16x16x32_bf16 v[134:137], v[140:143], v[160:163], v[134:137]
	v_mfma_f32_16x16x32_bf16 v[122:125], v[152:155], v[160:163], v[122:125]
	v_mfma_f32_16x16x32_bf16 v[110:113], v[140:143], v[168:171], v[110:113]
	v_mfma_f32_16x16x32_bf16 v[106:109], v[152:155], v[168:171], v[106:109]
	v_mfma_f32_16x16x32_bf16 v[94:97], v[140:143], v[186:189], v[94:97]
	v_mfma_f32_16x16x32_bf16 v[90:93], v[152:155], v[186:189], v[90:93]
	v_mfma_f32_16x16x32_bf16 v[78:81], v[140:143], v[198:201], v[78:81]
	v_mfma_f32_16x16x32_bf16 v[74:77], v[152:155], v[198:201], v[74:77]
	v_mfma_f32_16x16x32_bf16 v[134:137], v[148:151], v[164:167], v[134:137]
	v_mfma_f32_16x16x32_bf16 v[122:125], v[156:159], v[164:167], v[122:125]
	v_mfma_f32_16x16x32_bf16 v[110:113], v[148:151], v[172:175], v[110:113]
	v_mfma_f32_16x16x32_bf16 v[106:109], v[156:159], v[172:175], v[106:109]
	v_mfma_f32_16x16x32_bf16 v[94:97], v[148:151], v[190:193], v[94:97]
	v_mfma_f32_16x16x32_bf16 v[90:93], v[156:159], v[190:193], v[90:93]
	v_mfma_f32_16x16x32_bf16 v[78:81], v[148:151], v[202:205], v[78:81]
	v_mfma_f32_16x16x32_bf16 v[74:77], v[156:159], v[202:205], v[74:77]
	v_mfma_f32_16x16x32_bf16 v[118:121], v[206:209], v[160:163], v[118:121]
	v_mfma_f32_16x16x32_bf16 v[114:117], v[218:221], v[160:163], v[114:117]
	v_mfma_f32_16x16x32_bf16 v[102:105], v[206:209], v[168:171], v[102:105]
	v_mfma_f32_16x16x32_bf16 v[98:101], v[218:221], v[168:171], v[98:101]
	v_mfma_f32_16x16x32_bf16 v[86:89], v[206:209], v[186:189], v[86:89]
	v_mfma_f32_16x16x32_bf16 v[82:85], v[218:221], v[186:189], v[82:85]
	v_mfma_f32_16x16x32_bf16 v[70:73], v[206:209], v[198:201], v[70:73]
	v_mfma_f32_16x16x32_bf16 v[66:69], v[218:221], v[198:201], v[66:69]
	v_mfma_f32_16x16x32_bf16 v[118:121], v[214:217], v[164:167], v[118:121]
	v_mfma_f32_16x16x32_bf16 v[114:117], v[222:225], v[164:167], v[114:117]
	v_mfma_f32_16x16x32_bf16 v[102:105], v[214:217], v[172:175], v[102:105]
	v_mfma_f32_16x16x32_bf16 v[98:101], v[222:225], v[172:175], v[98:101]
	v_mfma_f32_16x16x32_bf16 v[86:89], v[214:217], v[190:193], v[86:89]
	v_mfma_f32_16x16x32_bf16 v[82:85], v[222:225], v[190:193], v[82:85]
	v_mfma_f32_16x16x32_bf16 v[70:73], v[214:217], v[202:205], v[70:73]
	v_mfma_f32_16x16x32_bf16 v[66:69], v[222:225], v[202:205], v[66:69]
	s_mov_b32 m0, s22
	v_lshl_add_u64 v[144:145], v[180:181], 0, s[70:71]
	s_barrier
; #define PG8_STAGE(bufoff, gbase, voff) do { _Pragma("unroll") for (int _i = 0; _i < 2; ++_i) \
;     __builtin_amdgcn_global_load_lds((const unsigned*)((const char*)(gbase) + (voff)[_i]), (LAS unsigned*)(lds + (bufoff) + ldsw + _i * 8192), 16, 0, 0); } while (0)
; #define PG8_LDA(dst, b, h) do { _Pragma("unroll") for (int m = 0; m < 4; ++m) _Pragma("unroll") for (int k = 0; k < 2; ++k) dst[m][k] = *(const LAS bf16x8*)(lds + PG8_SA(b, h) + aoff + m * 2048 + k * 1024); } while (0)
; #define PG8_MMA(ai, bj, At, Bt) do { __builtin_amdgcn_s_setprio(1); _Pragma("unroll") for (int m = 0; m < 4; ++m) _Pragma("unroll") for (int n = 0; n < 2; ++n) _Pragma("unroll") for (int k = 0; k < 2; ++k) \
;     acc[ai][bj][m][n] = __builtin_amdgcn_mfma_f32_16x16x32_bf16(Bt[n][k], At[m][k], acc[ai][bj][m][n], 0, 0, 0); __builtin_amdgcn_s_setprio(0); } while (0)
; #define PG8_WAIT_V(n) asm volatile("s_waitcnt vmcnt(" #n ")" ::: "memory")
; #define PG8_WAIT_L(n) asm volatile("s_waitcnt lgkmcnt(" #n ")" ::: "memory")
; #define PG8_BAR __builtin_amdgcn_s_barrier()
; #define PG8_SCHED __builtin_amdgcn_sched_barrier(0)
; template <class Epi, class Sched>
; DI void gemm_phase(LAS unsigned char* lds, const Gemm g, const Sched& S, const Epi& E) {
;     ...
;       PG8_LDA(At, 1, 1); PG8_STAGE(PG8_SA(1, 0), a3, voffA);
;       PG8_BAR; PG8_WAIT_L(0); PG8_MMA(1, 0, At, B0); PG8_BAR; PG8_SCHED;
;       PG8_STAGE(PG8_SB(1, 1), b3 + hstepB, voffB);
;       PG8_WAIT_V(6); PG8_BAR; PG8_MMA(1, 1, At, B1); PG8_BAR;
	ds_read_b128 v[160:163], v138 offset:49152
	ds_read_b128 v[164:167], v138 offset:50176
	ds_read_b128 v[168:171], v138 offset:51200
	ds_read_b128 v[172:175], v138 offset:52224
	ds_read_b128 v[186:189], v138 offset:53248
	ds_read_b128 v[190:193], v138 offset:54272
	ds_read_b128 v[198:201], v138 offset:55296
	ds_read_b128 v[202:205], v138 offset:56320
	global_load_lds_dwordx4 v[144:145], off
	v_lshl_add_u64 v[144:145], v[182:183], 0, s[70:71]
	s_mov_b32 m0, s23
	s_nop 0
	global_load_lds_dwordx4 v[144:145], off
	v_lshl_add_u64 v[230:231], v[230:231], 0, s[70:71]
	s_mov_b32 m0, s9
	s_nop 0
	global_load_lds_dwordx4 v[230:231], off
	v_lshl_add_u64 v[144:145], v[176:177], 0, s[70:71]
	s_add_i32 m0, s9, 0x2000
	s_nop 0
	global_load_lds_dwordx4 v[144:145], off
	s_add_i32 s8, s8, s17
	v_lshl_add_u64 v[232:233], v[184:185], 0, s[70:71]
	s_mov_b32 m0, s8
	s_nop 0
	global_load_lds_dwordx4 v[232:233], off
	v_lshl_add_u64 v[232:233], v[226:227], 0, s[70:71]
	s_add_i32 m0, s8, 0x2000
	s_nop 0
	global_load_lds_dwordx4 v[232:233], off
	s_waitcnt vmcnt(6)
	s_waitcnt lgkmcnt(0)
	s_barrier
	v_mfma_f32_16x16x32_bf16 v[62:65], v[140:143], v[160:163], v[62:65]
	v_mfma_f32_16x16x32_bf16 v[58:61], v[152:155], v[160:163], v[58:61]
	v_mfma_f32_16x16x32_bf16 v[50:53], v[140:143], v[168:171], v[50:53]
	v_mfma_f32_16x16x32_bf16 v[42:45], v[152:155], v[168:171], v[42:45]
	v_mfma_f32_16x16x32_bf16 v[34:37], v[140:143], v[186:189], v[34:37]
	v_mfma_f32_16x16x32_bf16 v[26:29], v[152:155], v[186:189], v[26:29]
	v_mfma_f32_16x16x32_bf16 v[18:21], v[140:143], v[198:201], v[18:21]
	v_mfma_f32_16x16x32_bf16 v[10:13], v[152:155], v[198:201], v[10:13]
	v_mfma_f32_16x16x32_bf16 v[62:65], v[148:151], v[164:167], v[62:65]
	v_mfma_f32_16x16x32_bf16 v[58:61], v[156:159], v[164:167], v[58:61]
	v_mfma_f32_16x16x32_bf16 v[50:53], v[148:151], v[172:175], v[50:53]
	v_mfma_f32_16x16x32_bf16 v[42:45], v[156:159], v[172:175], v[42:45]
	v_mfma_f32_16x16x32_bf16 v[34:37], v[148:151], v[190:193], v[34:37]
	v_mfma_f32_16x16x32_bf16 v[26:29], v[156:159], v[190:193], v[26:29]
	v_mfma_f32_16x16x32_bf16 v[18:21], v[148:151], v[202:205], v[18:21]
	v_mfma_f32_16x16x32_bf16 v[10:13], v[156:159], v[202:205], v[10:13]
	v_mfma_f32_16x16x32_bf16 v[54:57], v[206:209], v[160:163], v[54:57]
	v_mfma_f32_16x16x32_bf16 v[46:49], v[218:221], v[160:163], v[46:49]
	v_mfma_f32_16x16x32_bf16 v[38:41], v[206:209], v[168:171], v[38:41]
	v_mfma_f32_16x16x32_bf16 v[30:33], v[218:221], v[168:171], v[30:33]
	v_mfma_f32_16x16x32_bf16 v[22:25], v[206:209], v[186:189], v[22:25]
	v_mfma_f32_16x16x32_bf16 v[14:17], v[218:221], v[186:189], v[14:17]
	v_mfma_f32_16x16x32_bf16 v[6:9], v[206:209], v[198:201], v[6:9]
	v_mfma_f32_16x16x32_bf16 v[2:5], v[218:221], v[198:201], v[2:5]
	v_mfma_f32_16x16x32_bf16 v[54:57], v[214:217], v[164:167], v[54:57]
	v_mfma_f32_16x16x32_bf16 v[46:49], v[222:225], v[164:167], v[46:49]
	v_mfma_f32_16x16x32_bf16 v[38:41], v[214:217], v[172:175], v[38:41]
	v_mfma_f32_16x16x32_bf16 v[30:33], v[222:225], v[172:175], v[30:33]
	v_mfma_f32_16x16x32_bf16 v[22:25], v[214:217], v[190:193], v[22:25]
	v_mfma_f32_16x16x32_bf16 v[14:17], v[222:225], v[190:193], v[14:17]
	v_mfma_f32_16x16x32_bf16 v[6:9], v[214:217], v[202:205], v[6:9]
	v_mfma_f32_16x16x32_bf16 v[2:5], v[222:225], v[202:205], v[2:5]
	s_add_u32 s6, s6, 0x100
	s_addc_u32 s7, s7, 0
	s_cmp_ge_i32 s26, s24
	s_mov_b32 s8, s26
	s_barrier
	s_cbranch_scc0 .LBB0_491
	s_movk_i32 s27, 0xffd0
	s_movk_i32 s28, 0x2200
